# all per-section s_setprio toggles removed; one static s_setprio 1 for waves 4-7 (younger half) for the whole layer loop
# speedup vs baseline: 1.0087x; 1.0011x over previous
.LBB0_80:
	v_readfirstlane_b32 s0, v206
	s_cmpk_gt_i32 s0, 0xff
	s_cbranch_scc0 .Lsp_skip
	s_setprio 1

.LBB0_221:
	s_add_u32 s42, s38, 0xfffc0080
	s_addc_u32 s43, s39, -1
	s_add_i32 s61, 0, 0x10000
	s_cmp_eq_u32 s59, 12
	s_cselect_b32 s45, s11, s43
	s_cselect_b32 s44, s13, s42
	s_cselect_b32 s43, s55, s58
	s_cselect_b32 s42, s56, s57
	s_add_i32 s64, 0, 0x14000
	v_add_u32_e32 v156, s61, v150
	v_add_u32_e32 v172, s64, v150
	ds_read_b128 v[140:143], v156
	ds_read_b128 v[144:147], v156 offset:1024
	ds_read_b128 v[152:155], v156 offset:2048
	ds_read_b128 v[156:159], v156 offset:3072
	ds_read_b128 v[160:163], v172
	ds_read_b128 v[164:167], v172 offset:1024
	ds_read_b128 v[168:171], v172 offset:2048
	ds_read_b128 v[172:175], v172 offset:3072
	v_lshl_add_u64 v[218:219], s[38:39], 0, v[138:139]
	s_add_i32 m0, s33, 0xc000
	ds_read_b128 v[176:179], v151
	ds_read_b128 v[180:183], v151 offset:1024
	ds_read_b128 v[184:187], v151 offset:2048
	ds_read_b128 v[188:191], v151 offset:3072
	ds_read_b128 v[194:197], v151 offset:4096
	ds_read_b128 v[198:201], v151 offset:5120
	ds_read_b128 v[202:205], v151 offset:6144
	ds_read_b128 v[214:217], v151 offset:7168
	global_load_lds_dwordx4 v[218:219], off
	v_lshl_add_u64 v[218:219], s[38:39], 0, v[136:137]
	s_add_i32 m0, s33, 0xe000
	s_nop 0
	global_load_lds_dwordx4 v[218:219], off
	s_waitcnt vmcnt(8)
	s_waitcnt lgkmcnt(0)
	s_barrier
	s_waitcnt lgkmcnt(0)
	v_mfma_f32_16x16x32_bf16 v[124:127], v[140:143], v[176:179], v[124:127]
	v_mfma_f32_16x16x32_bf16 v[120:123], v[152:155], v[176:179], v[120:123]
	v_mfma_f32_16x16x32_bf16 v[108:111], v[140:143], v[184:187], v[108:111]
	v_mfma_f32_16x16x32_bf16 v[104:107], v[152:155], v[184:187], v[104:107]
	v_mfma_f32_16x16x32_bf16 v[92:95], v[140:143], v[194:197], v[92:95]
	v_mfma_f32_16x16x32_bf16 v[88:91], v[152:155], v[194:197], v[88:91]
	v_mfma_f32_16x16x32_bf16 v[76:79], v[140:143], v[202:205], v[76:79]
	v_mfma_f32_16x16x32_bf16 v[72:75], v[152:155], v[202:205], v[72:75]
	v_mfma_f32_16x16x32_bf16 v[124:127], v[144:147], v[180:183], v[124:127]
	v_mfma_f32_16x16x32_bf16 v[120:123], v[156:159], v[180:183], v[120:123]
	v_mfma_f32_16x16x32_bf16 v[108:111], v[144:147], v[188:191], v[108:111]
	v_mfma_f32_16x16x32_bf16 v[104:107], v[156:159], v[188:191], v[104:107]
	v_mfma_f32_16x16x32_bf16 v[92:95], v[144:147], v[198:201], v[92:95]
	v_mfma_f32_16x16x32_bf16 v[88:91], v[156:159], v[198:201], v[88:91]
	v_mfma_f32_16x16x32_bf16 v[76:79], v[144:147], v[214:217], v[76:79]
	v_mfma_f32_16x16x32_bf16 v[72:75], v[156:159], v[214:217], v[72:75]
	v_mfma_f32_16x16x32_bf16 v[116:119], v[160:163], v[176:179], v[116:119]
	v_mfma_f32_16x16x32_bf16 v[112:115], v[168:171], v[176:179], v[112:115]
	v_mfma_f32_16x16x32_bf16 v[100:103], v[160:163], v[184:187], v[100:103]
	v_mfma_f32_16x16x32_bf16 v[96:99], v[168:171], v[184:187], v[96:99]
	v_mfma_f32_16x16x32_bf16 v[84:87], v[160:163], v[194:197], v[84:87]
	v_mfma_f32_16x16x32_bf16 v[80:83], v[168:171], v[194:197], v[80:83]
	v_mfma_f32_16x16x32_bf16 v[68:71], v[160:163], v[202:205], v[68:71]
	v_mfma_f32_16x16x32_bf16 v[64:67], v[168:171], v[202:205], v[64:67]
	v_mfma_f32_16x16x32_bf16 v[116:119], v[164:167], v[180:183], v[116:119]
	v_mfma_f32_16x16x32_bf16 v[112:115], v[172:175], v[180:183], v[112:115]
	v_mfma_f32_16x16x32_bf16 v[100:103], v[164:167], v[188:191], v[100:103]
	v_mfma_f32_16x16x32_bf16 v[96:99], v[172:175], v[188:191], v[96:99]
	v_mfma_f32_16x16x32_bf16 v[84:87], v[164:167], v[198:201], v[84:87]
	v_mfma_f32_16x16x32_bf16 v[80:83], v[172:175], v[198:201], v[80:83]
	v_mfma_f32_16x16x32_bf16 v[68:71], v[164:167], v[214:217], v[68:71]
	v_mfma_f32_16x16x32_bf16 v[64:67], v[172:175], v[214:217], v[64:67]
	s_barrier
	s_add_i32 s61, s61, s27
	v_lshl_add_u64 v[218:219], s[42:43], 0, v[132:133]
	s_mov_b32 m0, s61
	ds_read_b128 v[176:179], v151 offset:16384
	ds_read_b128 v[180:183], v151 offset:17408
	ds_read_b128 v[184:187], v151 offset:18432
	ds_read_b128 v[188:191], v151 offset:19456
	ds_read_b128 v[194:197], v151 offset:20480
	ds_read_b128 v[198:201], v151 offset:21504
	ds_read_b128 v[202:205], v151 offset:22528
	ds_read_b128 v[214:217], v151 offset:23552
	global_load_lds_dwordx4 v[218:219], off
	s_add_i32 m0, s61, 0x2000
	s_add_u32 s62, s42, 0x40000
	v_lshl_add_u64 v[220:221], s[42:43], 0, v[128:129]
	s_addc_u32 s63, s43, 0
	s_add_i32 s61, s64, s27
	global_load_lds_dwordx4 v[220:221], off
	v_lshl_add_u64 v[222:223], s[62:63], 0, v[132:133]
	s_mov_b32 m0, s61
	v_lshl_add_u64 v[224:225], s[44:45], 0, v[130:131]
	global_load_lds_dwordx4 v[222:223], off
	v_lshl_add_u64 v[222:223], s[62:63], 0, v[128:129]
	s_add_i32 m0, s61, 0x2000
	s_nop 0
	global_load_lds_dwordx4 v[222:223], off
	v_lshl_add_u64 v[222:223], s[44:45], 0, v[134:135]
	s_mov_b32 m0, s33
	s_nop 0
	global_load_lds_dwordx4 v[222:223], off
	s_mov_b32 m0, s40
	s_nop 0
	global_load_lds_dwordx4 v[224:225], off
	s_waitcnt vmcnt(8)
	s_waitcnt lgkmcnt(0)
	s_barrier
	s_waitcnt lgkmcnt(0)
	v_mfma_f32_16x16x32_bf16 v[60:63], v[140:143], v[176:179], v[60:63]
	v_mfma_f32_16x16x32_bf16 v[56:59], v[152:155], v[176:179], v[56:59]
	v_mfma_f32_16x16x32_bf16 v[44:47], v[140:143], v[184:187], v[44:47]
	v_mfma_f32_16x16x32_bf16 v[40:43], v[152:155], v[184:187], v[40:43]
	v_mfma_f32_16x16x32_bf16 v[28:31], v[140:143], v[194:197], v[28:31]
	v_mfma_f32_16x16x32_bf16 v[24:27], v[152:155], v[194:197], v[24:27]
	v_mfma_f32_16x16x32_bf16 v[12:15], v[140:143], v[202:205], v[12:15]
	v_mfma_f32_16x16x32_bf16 v[8:11], v[152:155], v[202:205], v[8:11]
	v_mfma_f32_16x16x32_bf16 v[60:63], v[144:147], v[180:183], v[60:63]
	v_mfma_f32_16x16x32_bf16 v[56:59], v[156:159], v[180:183], v[56:59]
	v_mfma_f32_16x16x32_bf16 v[44:47], v[144:147], v[188:191], v[44:47]
	v_mfma_f32_16x16x32_bf16 v[40:43], v[156:159], v[188:191], v[40:43]
	v_mfma_f32_16x16x32_bf16 v[28:31], v[144:147], v[198:201], v[28:31]
	v_mfma_f32_16x16x32_bf16 v[24:27], v[156:159], v[198:201], v[24:27]
	v_mfma_f32_16x16x32_bf16 v[12:15], v[144:147], v[214:217], v[12:15]
	v_mfma_f32_16x16x32_bf16 v[8:11], v[156:159], v[214:217], v[8:11]
	v_mfma_f32_16x16x32_bf16 v[52:55], v[160:163], v[176:179], v[52:55]
	v_mfma_f32_16x16x32_bf16 v[48:51], v[168:171], v[176:179], v[48:51]
	v_mfma_f32_16x16x32_bf16 v[36:39], v[160:163], v[184:187], v[36:39]
	v_mfma_f32_16x16x32_bf16 v[32:35], v[168:171], v[184:187], v[32:35]
	v_mfma_f32_16x16x32_bf16 v[20:23], v[160:163], v[194:197], v[20:23]
	v_mfma_f32_16x16x32_bf16 v[16:19], v[168:171], v[194:197], v[16:19]
	v_mfma_f32_16x16x32_bf16 v[4:7], v[160:163], v[202:205], v[4:7]
	v_mfma_f32_16x16x32_bf16 v[0:3], v[168:171], v[202:205], v[0:3]
	v_mfma_f32_16x16x32_bf16 v[52:55], v[164:167], v[180:183], v[52:55]
	v_mfma_f32_16x16x32_bf16 v[48:51], v[172:175], v[180:183], v[48:51]
	v_mfma_f32_16x16x32_bf16 v[36:39], v[164:167], v[188:191], v[36:39]
	v_mfma_f32_16x16x32_bf16 v[32:35], v[172:175], v[188:191], v[32:35]
	v_mfma_f32_16x16x32_bf16 v[20:23], v[164:167], v[198:201], v[20:23]
	v_mfma_f32_16x16x32_bf16 v[16:19], v[172:175], v[198:201], v[16:19]
	v_mfma_f32_16x16x32_bf16 v[4:7], v[164:167], v[214:217], v[4:7]
	v_mfma_f32_16x16x32_bf16 v[0:3], v[172:175], v[214:217], v[0:3]
	s_barrier
	s_add_i32 s61, 0, 0x18000
	s_add_i32 s62, 0, 0x1c000
	v_add_u32_e32 v156, s61, v150
	v_add_u32_e32 v172, s62, v150
	ds_read_b128 v[140:143], v156
	ds_read_b128 v[144:147], v156 offset:1024
	ds_read_b128 v[152:155], v156 offset:2048
	ds_read_b128 v[156:159], v156 offset:3072
	ds_read_b128 v[160:163], v172
	ds_read_b128 v[164:167], v172 offset:1024
	ds_read_b128 v[168:171], v172 offset:2048
	ds_read_b128 v[172:175], v172 offset:3072
	s_add_u32 s44, s44, 0x40000
	s_addc_u32 s45, s45, 0
	s_mov_b32 m0, s46
	v_lshl_add_u64 v[226:227], s[44:45], 0, v[134:135]
	ds_read_b128 v[176:179], v151 offset:32768
	ds_read_b128 v[180:183], v151 offset:33792
	ds_read_b128 v[184:187], v151 offset:34816
	ds_read_b128 v[188:191], v151 offset:35840
	ds_read_b128 v[194:197], v151 offset:36864
	ds_read_b128 v[198:201], v151 offset:37888
	ds_read_b128 v[202:205], v151 offset:38912
	ds_read_b128 v[214:217], v151 offset:39936
	global_load_lds_dwordx4 v[226:227], off
	v_lshl_add_u64 v[226:227], s[44:45], 0, v[130:131]
	s_mov_b32 m0, s47
	s_nop 0
	global_load_lds_dwordx4 v[226:227], off
	s_waitcnt vmcnt(8)
	s_waitcnt lgkmcnt(0)
	s_barrier
	s_waitcnt lgkmcnt(0)
	v_mfma_f32_16x16x32_bf16 v[124:127], v[140:143], v[176:179], v[124:127]
	v_mfma_f32_16x16x32_bf16 v[120:123], v[152:155], v[176:179], v[120:123]
	v_mfma_f32_16x16x32_bf16 v[108:111], v[140:143], v[184:187], v[108:111]
	v_mfma_f32_16x16x32_bf16 v[104:107], v[152:155], v[184:187], v[104:107]
	v_mfma_f32_16x16x32_bf16 v[92:95], v[140:143], v[194:197], v[92:95]
	v_mfma_f32_16x16x32_bf16 v[88:91], v[152:155], v[194:197], v[88:91]
	v_mfma_f32_16x16x32_bf16 v[76:79], v[140:143], v[202:205], v[76:79]
	v_mfma_f32_16x16x32_bf16 v[72:75], v[152:155], v[202:205], v[72:75]
	v_mfma_f32_16x16x32_bf16 v[124:127], v[144:147], v[180:183], v[124:127]
	v_mfma_f32_16x16x32_bf16 v[120:123], v[156:159], v[180:183], v[120:123]
	v_mfma_f32_16x16x32_bf16 v[108:111], v[144:147], v[188:191], v[108:111]
	v_mfma_f32_16x16x32_bf16 v[104:107], v[156:159], v[188:191], v[104:107]
	v_mfma_f32_16x16x32_bf16 v[92:95], v[144:147], v[198:201], v[92:95]
	v_mfma_f32_16x16x32_bf16 v[88:91], v[156:159], v[198:201], v[88:91]
	v_mfma_f32_16x16x32_bf16 v[76:79], v[144:147], v[214:217], v[76:79]
	v_mfma_f32_16x16x32_bf16 v[72:75], v[156:159], v[214:217], v[72:75]
	v_mfma_f32_16x16x32_bf16 v[116:119], v[160:163], v[176:179], v[116:119]
	v_mfma_f32_16x16x32_bf16 v[112:115], v[168:171], v[176:179], v[112:115]
	v_mfma_f32_16x16x32_bf16 v[100:103], v[160:163], v[184:187], v[100:103]
	v_mfma_f32_16x16x32_bf16 v[96:99], v[168:171], v[184:187], v[96:99]
	v_mfma_f32_16x16x32_bf16 v[84:87], v[160:163], v[194:197], v[84:87]
	v_mfma_f32_16x16x32_bf16 v[80:83], v[168:171], v[194:197], v[80:83]
	v_mfma_f32_16x16x32_bf16 v[68:71], v[160:163], v[202:205], v[68:71]
	v_mfma_f32_16x16x32_bf16 v[64:67], v[168:171], v[202:205], v[64:67]
	v_mfma_f32_16x16x32_bf16 v[116:119], v[164:167], v[180:183], v[116:119]
	v_mfma_f32_16x16x32_bf16 v[112:115], v[172:175], v[180:183], v[112:115]
	v_mfma_f32_16x16x32_bf16 v[100:103], v[164:167], v[188:191], v[100:103]
	v_mfma_f32_16x16x32_bf16 v[96:99], v[172:175], v[188:191], v[96:99]
	v_mfma_f32_16x16x32_bf16 v[84:87], v[164:167], v[198:201], v[84:87]
	v_mfma_f32_16x16x32_bf16 v[80:83], v[172:175], v[198:201], v[80:83]
	v_mfma_f32_16x16x32_bf16 v[68:71], v[164:167], v[214:217], v[68:71]
	v_mfma_f32_16x16x32_bf16 v[64:67], v[172:175], v[214:217], v[64:67]
	s_barrier
	s_add_i32 s44, s61, s27
	v_lshl_add_u64 v[218:219], v[218:219], 0, s[76:77]
	s_mov_b32 m0, s44
	ds_read_b128 v[176:179], v151 offset:49152
	ds_read_b128 v[180:183], v151 offset:50176
	ds_read_b128 v[184:187], v151 offset:51200
	ds_read_b128 v[188:191], v151 offset:52224
	ds_read_b128 v[194:197], v151 offset:53248
	ds_read_b128 v[198:201], v151 offset:54272
	ds_read_b128 v[202:205], v151 offset:55296
	ds_read_b128 v[214:217], v151 offset:56320
	global_load_lds_dwordx4 v[218:219], off
	s_add_i32 m0, s44, 0x2000
	s_add_u32 s42, s42, 0x40080
	v_lshl_add_u64 v[218:219], v[220:221], 0, s[76:77]
	s_addc_u32 s43, s43, 0
	s_add_i32 s44, s62, s27
	global_load_lds_dwordx4 v[218:219], off
	v_lshl_add_u64 v[218:219], s[42:43], 0, v[132:133]
	s_mov_b32 m0, s44
	s_nop 0
	global_load_lds_dwordx4 v[218:219], off
	v_lshl_add_u64 v[218:219], s[42:43], 0, v[128:129]
	s_add_i32 m0, s44, 0x2000
	s_nop 0
	global_load_lds_dwordx4 v[218:219], off
	v_lshl_add_u64 v[218:219], v[222:223], 0, s[76:77]
	s_mov_b32 m0, s52
	s_nop 0
	global_load_lds_dwordx4 v[218:219], off
	v_lshl_add_u64 v[218:219], v[224:225], 0, s[76:77]
	s_mov_b32 m0, s53
	s_nop 0
	global_load_lds_dwordx4 v[218:219], off
	s_waitcnt vmcnt(8)
	s_waitcnt lgkmcnt(0)
	s_barrier
	s_waitcnt lgkmcnt(0)
	v_mfma_f32_16x16x32_bf16 v[60:63], v[140:143], v[176:179], v[60:63]
	v_mfma_f32_16x16x32_bf16 v[56:59], v[152:155], v[176:179], v[56:59]
	v_mfma_f32_16x16x32_bf16 v[44:47], v[140:143], v[184:187], v[44:47]
	v_mfma_f32_16x16x32_bf16 v[40:43], v[152:155], v[184:187], v[40:43]
	v_mfma_f32_16x16x32_bf16 v[28:31], v[140:143], v[194:197], v[28:31]
	v_mfma_f32_16x16x32_bf16 v[24:27], v[152:155], v[194:197], v[24:27]
	v_mfma_f32_16x16x32_bf16 v[12:15], v[140:143], v[202:205], v[12:15]
	v_mfma_f32_16x16x32_bf16 v[8:11], v[152:155], v[202:205], v[8:11]
	v_mfma_f32_16x16x32_bf16 v[60:63], v[144:147], v[180:183], v[60:63]
	v_mfma_f32_16x16x32_bf16 v[56:59], v[156:159], v[180:183], v[56:59]
	v_mfma_f32_16x16x32_bf16 v[44:47], v[144:147], v[188:191], v[44:47]
	v_mfma_f32_16x16x32_bf16 v[40:43], v[156:159], v[188:191], v[40:43]
	v_mfma_f32_16x16x32_bf16 v[28:31], v[144:147], v[198:201], v[28:31]
	v_mfma_f32_16x16x32_bf16 v[24:27], v[156:159], v[198:201], v[24:27]
	v_mfma_f32_16x16x32_bf16 v[12:15], v[144:147], v[214:217], v[12:15]
	v_mfma_f32_16x16x32_bf16 v[8:11], v[156:159], v[214:217], v[8:11]
	v_mfma_f32_16x16x32_bf16 v[52:55], v[160:163], v[176:179], v[52:55]
	v_mfma_f32_16x16x32_bf16 v[48:51], v[168:171], v[176:179], v[48:51]
	v_mfma_f32_16x16x32_bf16 v[36:39], v[160:163], v[184:187], v[36:39]
	v_mfma_f32_16x16x32_bf16 v[32:35], v[168:171], v[184:187], v[32:35]
	v_mfma_f32_16x16x32_bf16 v[20:23], v[160:163], v[194:197], v[20:23]
	v_mfma_f32_16x16x32_bf16 v[16:19], v[168:171], v[194:197], v[16:19]
	v_mfma_f32_16x16x32_bf16 v[4:7], v[160:163], v[202:205], v[4:7]
	v_mfma_f32_16x16x32_bf16 v[0:3], v[168:171], v[202:205], v[0:3]
	v_mfma_f32_16x16x32_bf16 v[52:55], v[164:167], v[180:183], v[52:55]
	v_mfma_f32_16x16x32_bf16 v[48:51], v[172:175], v[180:183], v[48:51]
	v_mfma_f32_16x16x32_bf16 v[36:39], v[164:167], v[188:191], v[36:39]
	v_mfma_f32_16x16x32_bf16 v[32:35], v[172:175], v[188:191], v[32:35]
	v_mfma_f32_16x16x32_bf16 v[20:23], v[164:167], v[198:201], v[20:23]
	v_mfma_f32_16x16x32_bf16 v[16:19], v[172:175], v[198:201], v[16:19]
	v_mfma_f32_16x16x32_bf16 v[4:7], v[164:167], v[214:217], v[4:7]
	v_mfma_f32_16x16x32_bf16 v[0:3], v[172:175], v[214:217], v[0:3]
	s_barrier
	s_add_i32 s59, s59, 2
	s_add_u32 s57, s57, 0x100
	s_addc_u32 s58, s58, 0
	s_add_u32 s38, s38, 0x100
	s_addc_u32 s39, s39, 0
	s_cmp_gt_u32 s59, 13
	s_cbranch_scc0 .LBB0_221
	s_and_b64 vcc, exec, s[8:9]
	s_cbranch_vccz .LBB0_224
	s_barrier

.LBB0_278:
	s_add_u32 s11, s38, s9
	s_addc_u32 s13, s39, 0
	s_add_u32 s54, s11, 0x100
	s_addc_u32 s55, s13, 0
	s_and_b64 s[52:53], s[46:47], exec
	s_cselect_b32 s55, s15, s55
	s_cselect_b32 s54, s14, s54
	s_add_u32 s9, s42, s9
	s_addc_u32 s52, s43, 0
	s_add_u32 s9, s9, 0x100
	s_addc_u32 s52, s52, 0
	s_add_i32 s83, 0, 0x10000
	s_and_b64 s[46:47], s[46:47], exec
	s_cselect_b32 s57, s17, s52
	s_cselect_b32 s56, s16, s9
	s_add_i32 s47, 0, 0x14000
	s_add_u32 s72, s11, 0x10080
	s_addc_u32 s73, s13, 0
	s_add_i32 s82, s83, s26
	s_add_i32 m0, s27, 0xc000
	s_add_i32 s85, s27, 0xe000
	s_add_i32 s68, s82, 0x2000
	s_add_u32 s62, s56, 0x40000
	v_add_u32_e32 v150, s83, v136
	v_add_u32_e32 v166, s47, v136
	s_addc_u32 s63, s57, 0
	s_add_i32 s81, s47, s26
	ds_read_b128 v[138:141], v150
	ds_read_b128 v[142:145], v150 offset:1024
	ds_read_b128 v[146:149], v150 offset:2048
	ds_read_b128 v[150:153], v150 offset:3072
	ds_read_b128 v[154:157], v166
	ds_read_b128 v[158:161], v166 offset:1024
	ds_read_b128 v[162:165], v166 offset:2048
	ds_read_b128 v[166:169], v166 offset:3072
	s_add_i32 s80, s81, 0x2000
	s_add_i32 s67, 0, 0x18000
	s_add_i32 s13, 0, 0x1c000
	s_add_u32 s52, s54, 0x10000
	s_addc_u32 s53, s55, 0
	s_add_i32 s11, s67, s26
	s_add_i32 s9, s11, 0x2000
	s_add_u32 s46, s56, 0x40080
	s_addc_u32 s47, s57, 0
	s_add_i32 s84, s13, s26
	s_add_i32 s83, s84, 0x2000
	v_lshl_add_u64 v[190:191], s[72:73], 0, v[132:133]
	ds_read_b128 v[170:173], v137
	ds_read_b128 v[174:177], v137 offset:1024
	ds_read_b128 v[178:181], v137 offset:2048
	ds_read_b128 v[182:185], v137 offset:3072
	ds_read_b128 v[186:189], v137 offset:4096
	ds_read_b128 v[194:197], v137 offset:5120
	ds_read_b128 v[198:201], v137 offset:6144
	ds_read_b128 v[202:205], v137 offset:7168
	global_load_lds_dwordx4 v[190:191], off
	v_lshl_add_u64 v[190:191], s[72:73], 0, v[130:131]
	s_mov_b32 m0, s85
	s_nop 0
	global_load_lds_dwordx4 v[190:191], off
	s_waitcnt vmcnt(8)
	s_waitcnt lgkmcnt(0)
	s_barrier
	s_waitcnt lgkmcnt(0)
	v_mfma_f32_16x16x32_bf16 v[124:127], v[138:141], v[170:173], v[124:127]
	v_mfma_f32_16x16x32_bf16 v[120:123], v[146:149], v[170:173], v[120:123]
	v_mfma_f32_16x16x32_bf16 v[116:119], v[138:141], v[178:181], v[116:119]
	v_mfma_f32_16x16x32_bf16 v[112:115], v[146:149], v[178:181], v[112:115]
	v_mfma_f32_16x16x32_bf16 v[100:103], v[138:141], v[186:189], v[100:103]
	v_mfma_f32_16x16x32_bf16 v[96:99], v[146:149], v[186:189], v[96:99]
	v_mfma_f32_16x16x32_bf16 v[84:87], v[138:141], v[198:201], v[84:87]
	v_mfma_f32_16x16x32_bf16 v[80:83], v[146:149], v[198:201], v[80:83]
	v_mfma_f32_16x16x32_bf16 v[124:127], v[142:145], v[174:177], v[124:127]
	v_mfma_f32_16x16x32_bf16 v[120:123], v[150:153], v[174:177], v[120:123]
	v_mfma_f32_16x16x32_bf16 v[116:119], v[142:145], v[182:185], v[116:119]
	v_mfma_f32_16x16x32_bf16 v[112:115], v[150:153], v[182:185], v[112:115]
	v_mfma_f32_16x16x32_bf16 v[100:103], v[142:145], v[194:197], v[100:103]
	v_mfma_f32_16x16x32_bf16 v[96:99], v[150:153], v[194:197], v[96:99]
	v_mfma_f32_16x16x32_bf16 v[84:87], v[142:145], v[202:205], v[84:87]
	v_mfma_f32_16x16x32_bf16 v[80:83], v[150:153], v[202:205], v[80:83]
	v_mfma_f32_16x16x32_bf16 v[108:111], v[154:157], v[170:173], v[108:111]
	v_mfma_f32_16x16x32_bf16 v[104:107], v[162:165], v[170:173], v[104:107]
	v_mfma_f32_16x16x32_bf16 v[92:95], v[154:157], v[178:181], v[92:95]
	v_mfma_f32_16x16x32_bf16 v[88:91], v[162:165], v[178:181], v[88:91]
	v_mfma_f32_16x16x32_bf16 v[76:79], v[154:157], v[186:189], v[76:79]
	v_mfma_f32_16x16x32_bf16 v[72:75], v[162:165], v[186:189], v[72:75]
	v_mfma_f32_16x16x32_bf16 v[68:71], v[154:157], v[198:201], v[68:71]
	v_mfma_f32_16x16x32_bf16 v[64:67], v[162:165], v[198:201], v[64:67]
	v_mfma_f32_16x16x32_bf16 v[108:111], v[158:161], v[174:177], v[108:111]
	v_mfma_f32_16x16x32_bf16 v[104:107], v[166:169], v[174:177], v[104:107]
	v_mfma_f32_16x16x32_bf16 v[92:95], v[158:161], v[182:185], v[92:95]
	v_mfma_f32_16x16x32_bf16 v[88:91], v[166:169], v[182:185], v[88:91]
	v_mfma_f32_16x16x32_bf16 v[76:79], v[158:161], v[194:197], v[76:79]
	v_mfma_f32_16x16x32_bf16 v[72:75], v[166:169], v[194:197], v[72:75]
	v_mfma_f32_16x16x32_bf16 v[68:71], v[158:161], v[202:205], v[68:71]
	v_mfma_f32_16x16x32_bf16 v[64:67], v[166:169], v[202:205], v[64:67]
	s_barrier
	s_mov_b32 m0, s82
	v_lshl_add_u64 v[190:191], s[56:57], 0, v[192:193]
	ds_read_b128 v[170:173], v137 offset:16384
	ds_read_b128 v[174:177], v137 offset:17408
	ds_read_b128 v[178:181], v137 offset:18432
	ds_read_b128 v[182:185], v137 offset:19456
	ds_read_b128 v[186:189], v137 offset:20480
	ds_read_b128 v[194:197], v137 offset:21504
	ds_read_b128 v[198:201], v137 offset:22528
	ds_read_b128 v[202:205], v137 offset:23552
	global_load_lds_dwordx4 v[190:191], off
	v_lshl_add_u64 v[214:215], s[56:57], 0, v[128:129]
	s_mov_b32 m0, s68
	v_lshl_add_u64 v[216:217], s[62:63], 0, v[192:193]
	global_load_lds_dwordx4 v[214:215], off
	s_mov_b32 m0, s81
	v_lshl_add_u64 v[218:219], s[54:55], 0, v[130:131]
	global_load_lds_dwordx4 v[216:217], off
	v_lshl_add_u64 v[216:217], s[62:63], 0, v[128:129]
	s_mov_b32 m0, s80
	s_nop 0
	global_load_lds_dwordx4 v[216:217], off
	v_lshl_add_u64 v[216:217], s[54:55], 0, v[132:133]
	s_mov_b32 m0, s27
	s_nop 0
	global_load_lds_dwordx4 v[216:217], off
	s_mov_b32 m0, s33
	s_nop 0
	global_load_lds_dwordx4 v[218:219], off
	s_waitcnt vmcnt(8)
	s_waitcnt lgkmcnt(0)
	s_barrier
	s_waitcnt lgkmcnt(0)
	v_mfma_f32_16x16x32_bf16 v[60:63], v[138:141], v[170:173], v[60:63]
	v_mfma_f32_16x16x32_bf16 v[56:59], v[146:149], v[170:173], v[56:59]
	v_mfma_f32_16x16x32_bf16 v[52:55], v[138:141], v[178:181], v[52:55]
	v_mfma_f32_16x16x32_bf16 v[48:51], v[146:149], v[178:181], v[48:51]
	v_mfma_f32_16x16x32_bf16 v[36:39], v[138:141], v[186:189], v[36:39]
	v_mfma_f32_16x16x32_bf16 v[32:35], v[146:149], v[186:189], v[32:35]
	v_mfma_f32_16x16x32_bf16 v[20:23], v[138:141], v[198:201], v[20:23]
	v_mfma_f32_16x16x32_bf16 v[16:19], v[146:149], v[198:201], v[16:19]
	v_mfma_f32_16x16x32_bf16 v[60:63], v[142:145], v[174:177], v[60:63]
	v_mfma_f32_16x16x32_bf16 v[56:59], v[150:153], v[174:177], v[56:59]
	v_mfma_f32_16x16x32_bf16 v[52:55], v[142:145], v[182:185], v[52:55]
	v_mfma_f32_16x16x32_bf16 v[48:51], v[150:153], v[182:185], v[48:51]
	v_mfma_f32_16x16x32_bf16 v[36:39], v[142:145], v[194:197], v[36:39]
	v_mfma_f32_16x16x32_bf16 v[32:35], v[150:153], v[194:197], v[32:35]
	v_mfma_f32_16x16x32_bf16 v[20:23], v[142:145], v[202:205], v[20:23]
	v_mfma_f32_16x16x32_bf16 v[16:19], v[150:153], v[202:205], v[16:19]
	v_mfma_f32_16x16x32_bf16 v[44:47], v[154:157], v[170:173], v[44:47]
	v_mfma_f32_16x16x32_bf16 v[40:43], v[162:165], v[170:173], v[40:43]
	v_mfma_f32_16x16x32_bf16 v[28:31], v[154:157], v[178:181], v[28:31]
	v_mfma_f32_16x16x32_bf16 v[24:27], v[162:165], v[178:181], v[24:27]
	v_mfma_f32_16x16x32_bf16 v[12:15], v[154:157], v[186:189], v[12:15]
	v_mfma_f32_16x16x32_bf16 v[8:11], v[162:165], v[186:189], v[8:11]
	v_mfma_f32_16x16x32_bf16 v[4:7], v[154:157], v[198:201], v[4:7]
	v_mfma_f32_16x16x32_bf16 v[0:3], v[162:165], v[198:201], v[0:3]
	v_mfma_f32_16x16x32_bf16 v[44:47], v[158:161], v[174:177], v[44:47]
	v_mfma_f32_16x16x32_bf16 v[40:43], v[166:169], v[174:177], v[40:43]
	v_mfma_f32_16x16x32_bf16 v[28:31], v[158:161], v[182:185], v[28:31]
	v_mfma_f32_16x16x32_bf16 v[24:27], v[166:169], v[182:185], v[24:27]
	v_mfma_f32_16x16x32_bf16 v[12:15], v[158:161], v[194:197], v[12:15]
	v_mfma_f32_16x16x32_bf16 v[8:11], v[166:169], v[194:197], v[8:11]
	v_mfma_f32_16x16x32_bf16 v[4:7], v[158:161], v[202:205], v[4:7]
	v_mfma_f32_16x16x32_bf16 v[0:3], v[166:169], v[202:205], v[0:3]
	s_barrier
	v_add_u32_e32 v150, s67, v136
	v_add_u32_e32 v166, s13, v136
	ds_read_b128 v[138:141], v150
	ds_read_b128 v[142:145], v150 offset:1024
	ds_read_b128 v[146:149], v150 offset:2048
	ds_read_b128 v[150:153], v150 offset:3072
	ds_read_b128 v[154:157], v166
	ds_read_b128 v[158:161], v166 offset:1024
	ds_read_b128 v[162:165], v166 offset:2048
	ds_read_b128 v[166:169], v166 offset:3072
	s_mov_b32 m0, s48
	v_lshl_add_u64 v[220:221], s[52:53], 0, v[132:133]
	ds_read_b128 v[170:173], v137 offset:32768
	ds_read_b128 v[174:177], v137 offset:33792
	ds_read_b128 v[178:181], v137 offset:34816
	ds_read_b128 v[182:185], v137 offset:35840
	ds_read_b128 v[186:189], v137 offset:36864
	ds_read_b128 v[194:197], v137 offset:37888
	ds_read_b128 v[198:201], v137 offset:38912
	ds_read_b128 v[202:205], v137 offset:39936
	global_load_lds_dwordx4 v[220:221], off
	v_lshl_add_u64 v[220:221], s[52:53], 0, v[130:131]
	s_mov_b32 m0, s49
	s_nop 0
	global_load_lds_dwordx4 v[220:221], off
	s_waitcnt vmcnt(8)
	s_waitcnt lgkmcnt(0)
	s_barrier
	s_waitcnt lgkmcnt(0)
	v_mfma_f32_16x16x32_bf16 v[124:127], v[138:141], v[170:173], v[124:127]
	v_mfma_f32_16x16x32_bf16 v[120:123], v[146:149], v[170:173], v[120:123]
	v_mfma_f32_16x16x32_bf16 v[116:119], v[138:141], v[178:181], v[116:119]
	v_mfma_f32_16x16x32_bf16 v[112:115], v[146:149], v[178:181], v[112:115]
	v_mfma_f32_16x16x32_bf16 v[100:103], v[138:141], v[186:189], v[100:103]
	v_mfma_f32_16x16x32_bf16 v[96:99], v[146:149], v[186:189], v[96:99]
	v_mfma_f32_16x16x32_bf16 v[84:87], v[138:141], v[198:201], v[84:87]
	v_mfma_f32_16x16x32_bf16 v[80:83], v[146:149], v[198:201], v[80:83]
	v_mfma_f32_16x16x32_bf16 v[124:127], v[142:145], v[174:177], v[124:127]
	v_mfma_f32_16x16x32_bf16 v[120:123], v[150:153], v[174:177], v[120:123]
	v_mfma_f32_16x16x32_bf16 v[116:119], v[142:145], v[182:185], v[116:119]
	v_mfma_f32_16x16x32_bf16 v[112:115], v[150:153], v[182:185], v[112:115]
	v_mfma_f32_16x16x32_bf16 v[100:103], v[142:145], v[194:197], v[100:103]
	v_mfma_f32_16x16x32_bf16 v[96:99], v[150:153], v[194:197], v[96:99]
	v_mfma_f32_16x16x32_bf16 v[84:87], v[142:145], v[202:205], v[84:87]
	v_mfma_f32_16x16x32_bf16 v[80:83], v[150:153], v[202:205], v[80:83]
	v_mfma_f32_16x16x32_bf16 v[108:111], v[154:157], v[170:173], v[108:111]
	v_mfma_f32_16x16x32_bf16 v[104:107], v[162:165], v[170:173], v[104:107]
	v_mfma_f32_16x16x32_bf16 v[92:95], v[154:157], v[178:181], v[92:95]
	v_mfma_f32_16x16x32_bf16 v[88:91], v[162:165], v[178:181], v[88:91]
	v_mfma_f32_16x16x32_bf16 v[76:79], v[154:157], v[186:189], v[76:79]
	v_mfma_f32_16x16x32_bf16 v[72:75], v[162:165], v[186:189], v[72:75]
	v_mfma_f32_16x16x32_bf16 v[68:71], v[154:157], v[198:201], v[68:71]
	v_mfma_f32_16x16x32_bf16 v[64:67], v[162:165], v[198:201], v[64:67]
	v_mfma_f32_16x16x32_bf16 v[108:111], v[158:161], v[174:177], v[108:111]
	v_mfma_f32_16x16x32_bf16 v[104:107], v[166:169], v[174:177], v[104:107]
	v_mfma_f32_16x16x32_bf16 v[92:95], v[158:161], v[182:185], v[92:95]
	v_mfma_f32_16x16x32_bf16 v[88:91], v[166:169], v[182:185], v[88:91]
	v_mfma_f32_16x16x32_bf16 v[76:79], v[158:161], v[194:197], v[76:79]
	v_mfma_f32_16x16x32_bf16 v[72:75], v[166:169], v[194:197], v[72:75]
	v_mfma_f32_16x16x32_bf16 v[68:71], v[158:161], v[202:205], v[68:71]
	v_mfma_f32_16x16x32_bf16 v[64:67], v[166:169], v[202:205], v[64:67]
	s_barrier
	s_mov_b32 m0, s11
	v_lshl_add_u64 v[190:191], v[190:191], 0, s[76:77]
	ds_read_b128 v[170:173], v137 offset:49152
	ds_read_b128 v[174:177], v137 offset:50176
	ds_read_b128 v[178:181], v137 offset:51200
	ds_read_b128 v[182:185], v137 offset:52224
	ds_read_b128 v[186:189], v137 offset:53248
	ds_read_b128 v[194:197], v137 offset:54272
	ds_read_b128 v[198:201], v137 offset:55296
	ds_read_b128 v[202:205], v137 offset:56320
	global_load_lds_dwordx4 v[190:191], off
	v_lshl_add_u64 v[190:191], v[214:215], 0, s[76:77]
	s_mov_b32 m0, s9
	s_nop 0
	global_load_lds_dwordx4 v[190:191], off
	v_lshl_add_u64 v[190:191], s[46:47], 0, v[192:193]
	s_mov_b32 m0, s84
	s_nop 0
	global_load_lds_dwordx4 v[190:191], off
	v_lshl_add_u64 v[190:191], s[46:47], 0, v[128:129]
	s_mov_b32 m0, s83
	s_nop 0
	global_load_lds_dwordx4 v[190:191], off
	v_lshl_add_u64 v[190:191], v[216:217], 0, s[76:77]
	s_mov_b32 m0, s59
	s_nop 0
	global_load_lds_dwordx4 v[190:191], off
	v_lshl_add_u64 v[190:191], v[218:219], 0, s[76:77]
	s_mov_b32 m0, s61
	s_nop 0
	global_load_lds_dwordx4 v[190:191], off
	s_waitcnt vmcnt(8)
	s_waitcnt lgkmcnt(0)
	s_barrier
	s_waitcnt lgkmcnt(0)
	v_mfma_f32_16x16x32_bf16 v[60:63], v[138:141], v[170:173], v[60:63]
	v_mfma_f32_16x16x32_bf16 v[56:59], v[146:149], v[170:173], v[56:59]
	v_mfma_f32_16x16x32_bf16 v[52:55], v[138:141], v[178:181], v[52:55]
	v_mfma_f32_16x16x32_bf16 v[48:51], v[146:149], v[178:181], v[48:51]
	v_mfma_f32_16x16x32_bf16 v[36:39], v[138:141], v[186:189], v[36:39]
	v_mfma_f32_16x16x32_bf16 v[32:35], v[146:149], v[186:189], v[32:35]
	v_mfma_f32_16x16x32_bf16 v[20:23], v[138:141], v[198:201], v[20:23]
	v_mfma_f32_16x16x32_bf16 v[16:19], v[146:149], v[198:201], v[16:19]
	v_mfma_f32_16x16x32_bf16 v[60:63], v[142:145], v[174:177], v[60:63]
	v_mfma_f32_16x16x32_bf16 v[56:59], v[150:153], v[174:177], v[56:59]
	v_mfma_f32_16x16x32_bf16 v[52:55], v[142:145], v[182:185], v[52:55]
	v_mfma_f32_16x16x32_bf16 v[48:51], v[150:153], v[182:185], v[48:51]
	v_mfma_f32_16x16x32_bf16 v[36:39], v[142:145], v[194:197], v[36:39]
	v_mfma_f32_16x16x32_bf16 v[32:35], v[150:153], v[194:197], v[32:35]
	v_mfma_f32_16x16x32_bf16 v[20:23], v[142:145], v[202:205], v[20:23]
	v_mfma_f32_16x16x32_bf16 v[16:19], v[150:153], v[202:205], v[16:19]
	v_mfma_f32_16x16x32_bf16 v[44:47], v[154:157], v[170:173], v[44:47]
	v_mfma_f32_16x16x32_bf16 v[40:43], v[162:165], v[170:173], v[40:43]
	v_mfma_f32_16x16x32_bf16 v[28:31], v[154:157], v[178:181], v[28:31]
	v_mfma_f32_16x16x32_bf16 v[24:27], v[162:165], v[178:181], v[24:27]
	v_mfma_f32_16x16x32_bf16 v[12:15], v[154:157], v[186:189], v[12:15]
	v_mfma_f32_16x16x32_bf16 v[8:11], v[162:165], v[186:189], v[8:11]
	v_mfma_f32_16x16x32_bf16 v[4:7], v[154:157], v[198:201], v[4:7]
	v_mfma_f32_16x16x32_bf16 v[0:3], v[162:165], v[198:201], v[0:3]
	v_mfma_f32_16x16x32_bf16 v[44:47], v[158:161], v[174:177], v[44:47]
	v_mfma_f32_16x16x32_bf16 v[40:43], v[166:169], v[174:177], v[40:43]
	v_mfma_f32_16x16x32_bf16 v[28:31], v[158:161], v[182:185], v[28:31]
	v_mfma_f32_16x16x32_bf16 v[24:27], v[166:169], v[182:185], v[24:27]
	v_mfma_f32_16x16x32_bf16 v[12:15], v[158:161], v[194:197], v[12:15]
	v_mfma_f32_16x16x32_bf16 v[8:11], v[166:169], v[194:197], v[8:11]
	v_mfma_f32_16x16x32_bf16 v[4:7], v[158:161], v[202:205], v[4:7]
	v_mfma_f32_16x16x32_bf16 v[0:3], v[166:169], v[202:205], v[0:3]
	s_barrier
	s_movk_i32 s9, 0x100
	s_andn2_b64 vcc, exec, s[44:45]
	s_mov_b64 s[46:47], -1
	s_mov_b64 s[44:45], 0
	s_cbranch_vccz .LBB0_278
	s_and_b64 vcc, exec, s[2:3]
	s_cbranch_vccz .LBB0_281
	s_barrier

.LBB0_299:
	s_add_u32 s14, s12, 0xfffc0080
	s_addc_u32 s15, s13, -1
	s_add_i32 s40, 0, 0x10000
	s_cmp_eq_u32 s39, 12
	s_cselect_b32 s17, s9, s15
	s_cselect_b32 s16, s11, s14
	s_cselect_b32 s15, s30, s38
	s_cselect_b32 s14, s31, s33
	s_add_i32 s52, 0, 0x14000
	v_add_u32_e32 v140, s40, v178
	v_add_u32_e32 v168, s52, v178
	ds_read_b128 v[128:131], v140
	ds_read_b128 v[132:135], v140 offset:1024
	ds_read_b128 v[136:139], v140 offset:2048
	ds_read_b128 v[140:143], v140 offset:3072
	ds_read_b128 v[156:159], v168
	ds_read_b128 v[160:163], v168 offset:1024
	ds_read_b128 v[164:167], v168 offset:2048
	ds_read_b128 v[168:171], v168 offset:3072
	v_lshl_add_u64 v[218:219], s[12:13], 0, v[154:155]
	s_add_i32 m0, s48, 0xc000
	ds_read_b128 v[172:175], v179
	ds_read_b128 v[180:183], v179 offset:1024
	ds_read_b128 v[184:187], v179 offset:2048
	ds_read_b128 v[188:191], v179 offset:3072
	ds_read_b128 v[194:197], v179 offset:4096
	ds_read_b128 v[198:201], v179 offset:5120
	ds_read_b128 v[202:205], v179 offset:6144
	ds_read_b128 v[214:217], v179 offset:7168
	global_load_lds_dwordx4 v[218:219], off
	v_lshl_add_u64 v[218:219], s[12:13], 0, v[152:153]
	s_add_i32 m0, s48, 0xe000
	s_nop 0
	global_load_lds_dwordx4 v[218:219], off
	s_waitcnt vmcnt(8)
	s_waitcnt lgkmcnt(0)
	s_barrier
	s_waitcnt lgkmcnt(0)
	v_mfma_f32_16x16x32_bf16 v[124:127], v[128:131], v[172:175], v[124:127]
	v_mfma_f32_16x16x32_bf16 v[120:123], v[136:139], v[172:175], v[120:123]
	v_mfma_f32_16x16x32_bf16 v[108:111], v[128:131], v[184:187], v[108:111]
	v_mfma_f32_16x16x32_bf16 v[104:107], v[136:139], v[184:187], v[104:107]
	v_mfma_f32_16x16x32_bf16 v[92:95], v[128:131], v[194:197], v[92:95]
	v_mfma_f32_16x16x32_bf16 v[88:91], v[136:139], v[194:197], v[88:91]
	v_mfma_f32_16x16x32_bf16 v[76:79], v[128:131], v[202:205], v[76:79]
	v_mfma_f32_16x16x32_bf16 v[72:75], v[136:139], v[202:205], v[72:75]
	v_mfma_f32_16x16x32_bf16 v[124:127], v[132:135], v[180:183], v[124:127]
	v_mfma_f32_16x16x32_bf16 v[120:123], v[140:143], v[180:183], v[120:123]
	v_mfma_f32_16x16x32_bf16 v[108:111], v[132:135], v[188:191], v[108:111]
	v_mfma_f32_16x16x32_bf16 v[104:107], v[140:143], v[188:191], v[104:107]
	v_mfma_f32_16x16x32_bf16 v[92:95], v[132:135], v[198:201], v[92:95]
	v_mfma_f32_16x16x32_bf16 v[88:91], v[140:143], v[198:201], v[88:91]
	v_mfma_f32_16x16x32_bf16 v[76:79], v[132:135], v[214:217], v[76:79]
	v_mfma_f32_16x16x32_bf16 v[72:75], v[140:143], v[214:217], v[72:75]
	v_mfma_f32_16x16x32_bf16 v[116:119], v[156:159], v[172:175], v[116:119]
	v_mfma_f32_16x16x32_bf16 v[112:115], v[164:167], v[172:175], v[112:115]
	v_mfma_f32_16x16x32_bf16 v[100:103], v[156:159], v[184:187], v[100:103]
	v_mfma_f32_16x16x32_bf16 v[96:99], v[164:167], v[184:187], v[96:99]
	v_mfma_f32_16x16x32_bf16 v[84:87], v[156:159], v[194:197], v[84:87]
	v_mfma_f32_16x16x32_bf16 v[80:83], v[164:167], v[194:197], v[80:83]
	v_mfma_f32_16x16x32_bf16 v[68:71], v[156:159], v[202:205], v[68:71]
	v_mfma_f32_16x16x32_bf16 v[64:67], v[164:167], v[202:205], v[64:67]
	v_mfma_f32_16x16x32_bf16 v[116:119], v[160:163], v[180:183], v[116:119]
	v_mfma_f32_16x16x32_bf16 v[112:115], v[168:171], v[180:183], v[112:115]
	v_mfma_f32_16x16x32_bf16 v[100:103], v[160:163], v[188:191], v[100:103]
	v_mfma_f32_16x16x32_bf16 v[96:99], v[168:171], v[188:191], v[96:99]
	v_mfma_f32_16x16x32_bf16 v[84:87], v[160:163], v[198:201], v[84:87]
	v_mfma_f32_16x16x32_bf16 v[80:83], v[168:171], v[198:201], v[80:83]
	v_mfma_f32_16x16x32_bf16 v[68:71], v[160:163], v[214:217], v[68:71]
	v_mfma_f32_16x16x32_bf16 v[64:67], v[168:171], v[214:217], v[64:67]
	s_barrier
	s_add_i32 s40, s40, s61
	v_lshl_add_u64 v[218:219], s[14:15], 0, v[148:149]
	s_mov_b32 m0, s40
	ds_read_b128 v[172:175], v179 offset:16384
	ds_read_b128 v[180:183], v179 offset:17408
	ds_read_b128 v[184:187], v179 offset:18432
	ds_read_b128 v[188:191], v179 offset:19456
	ds_read_b128 v[194:197], v179 offset:20480
	ds_read_b128 v[198:201], v179 offset:21504
	ds_read_b128 v[202:205], v179 offset:22528
	ds_read_b128 v[214:217], v179 offset:23552
	global_load_lds_dwordx4 v[218:219], off
	s_add_i32 m0, s40, 0x2000
	s_add_u32 s44, s14, 0x40000
	v_lshl_add_u64 v[220:221], s[14:15], 0, v[144:145]
	s_addc_u32 s45, s15, 0
	s_add_i32 s40, s52, s61
	global_load_lds_dwordx4 v[220:221], off
	v_lshl_add_u64 v[222:223], s[44:45], 0, v[148:149]
	s_mov_b32 m0, s40
	v_lshl_add_u64 v[224:225], s[16:17], 0, v[146:147]
	global_load_lds_dwordx4 v[222:223], off
	v_lshl_add_u64 v[222:223], s[44:45], 0, v[144:145]
	s_add_i32 m0, s40, 0x2000
	s_nop 0
	global_load_lds_dwordx4 v[222:223], off
	v_lshl_add_u64 v[222:223], s[16:17], 0, v[150:151]
	s_mov_b32 m0, s48
	s_nop 0
	global_load_lds_dwordx4 v[222:223], off
	s_mov_b32 m0, s49
	s_nop 0
	global_load_lds_dwordx4 v[224:225], off
	s_waitcnt vmcnt(8)
	s_waitcnt lgkmcnt(0)
	s_barrier
	s_waitcnt lgkmcnt(0)
	v_mfma_f32_16x16x32_bf16 v[60:63], v[128:131], v[172:175], v[60:63]
	v_mfma_f32_16x16x32_bf16 v[56:59], v[136:139], v[172:175], v[56:59]
	v_mfma_f32_16x16x32_bf16 v[44:47], v[128:131], v[184:187], v[44:47]
	v_mfma_f32_16x16x32_bf16 v[40:43], v[136:139], v[184:187], v[40:43]
	v_mfma_f32_16x16x32_bf16 v[28:31], v[128:131], v[194:197], v[28:31]
	v_mfma_f32_16x16x32_bf16 v[24:27], v[136:139], v[194:197], v[24:27]
	v_mfma_f32_16x16x32_bf16 v[12:15], v[128:131], v[202:205], v[12:15]
	v_mfma_f32_16x16x32_bf16 v[8:11], v[136:139], v[202:205], v[8:11]
	v_mfma_f32_16x16x32_bf16 v[60:63], v[132:135], v[180:183], v[60:63]
	v_mfma_f32_16x16x32_bf16 v[56:59], v[140:143], v[180:183], v[56:59]
	v_mfma_f32_16x16x32_bf16 v[44:47], v[132:135], v[188:191], v[44:47]
	v_mfma_f32_16x16x32_bf16 v[40:43], v[140:143], v[188:191], v[40:43]
	v_mfma_f32_16x16x32_bf16 v[28:31], v[132:135], v[198:201], v[28:31]
	v_mfma_f32_16x16x32_bf16 v[24:27], v[140:143], v[198:201], v[24:27]
	v_mfma_f32_16x16x32_bf16 v[12:15], v[132:135], v[214:217], v[12:15]
	v_mfma_f32_16x16x32_bf16 v[8:11], v[140:143], v[214:217], v[8:11]
	v_mfma_f32_16x16x32_bf16 v[52:55], v[156:159], v[172:175], v[52:55]
	v_mfma_f32_16x16x32_bf16 v[48:51], v[164:167], v[172:175], v[48:51]
	v_mfma_f32_16x16x32_bf16 v[36:39], v[156:159], v[184:187], v[36:39]
	v_mfma_f32_16x16x32_bf16 v[32:35], v[164:167], v[184:187], v[32:35]
	v_mfma_f32_16x16x32_bf16 v[20:23], v[156:159], v[194:197], v[20:23]
	v_mfma_f32_16x16x32_bf16 v[16:19], v[164:167], v[194:197], v[16:19]
	v_mfma_f32_16x16x32_bf16 v[4:7], v[156:159], v[202:205], v[4:7]
	v_mfma_f32_16x16x32_bf16 v[0:3], v[164:167], v[202:205], v[0:3]
	v_mfma_f32_16x16x32_bf16 v[52:55], v[160:163], v[180:183], v[52:55]
	v_mfma_f32_16x16x32_bf16 v[48:51], v[168:171], v[180:183], v[48:51]
	v_mfma_f32_16x16x32_bf16 v[36:39], v[160:163], v[188:191], v[36:39]
	v_mfma_f32_16x16x32_bf16 v[32:35], v[168:171], v[188:191], v[32:35]
	v_mfma_f32_16x16x32_bf16 v[20:23], v[160:163], v[198:201], v[20:23]
	v_mfma_f32_16x16x32_bf16 v[16:19], v[168:171], v[198:201], v[16:19]
	v_mfma_f32_16x16x32_bf16 v[4:7], v[160:163], v[214:217], v[4:7]
	v_mfma_f32_16x16x32_bf16 v[0:3], v[168:171], v[214:217], v[0:3]
	s_barrier
	s_add_i32 s40, 0, 0x18000
	s_add_i32 s44, 0, 0x1c000
	v_add_u32_e32 v140, s40, v178
	v_add_u32_e32 v168, s44, v178
	ds_read_b128 v[128:131], v140
	ds_read_b128 v[132:135], v140 offset:1024
	ds_read_b128 v[136:139], v140 offset:2048
	ds_read_b128 v[140:143], v140 offset:3072
	ds_read_b128 v[156:159], v168
	ds_read_b128 v[160:163], v168 offset:1024
	ds_read_b128 v[164:167], v168 offset:2048
	ds_read_b128 v[168:171], v168 offset:3072
	s_add_u32 s16, s16, 0x40000
	s_addc_u32 s17, s17, 0
	s_mov_b32 m0, s58
	v_lshl_add_u64 v[226:227], s[16:17], 0, v[150:151]
	ds_read_b128 v[172:175], v179 offset:32768
	ds_read_b128 v[180:183], v179 offset:33792
	ds_read_b128 v[184:187], v179 offset:34816
	ds_read_b128 v[188:191], v179 offset:35840
	ds_read_b128 v[194:197], v179 offset:36864
	ds_read_b128 v[198:201], v179 offset:37888
	ds_read_b128 v[202:205], v179 offset:38912
	ds_read_b128 v[214:217], v179 offset:39936
	global_load_lds_dwordx4 v[226:227], off
	v_lshl_add_u64 v[226:227], s[16:17], 0, v[146:147]
	s_mov_b32 m0, s59
	s_nop 0
	global_load_lds_dwordx4 v[226:227], off
	s_waitcnt vmcnt(8)
	s_waitcnt lgkmcnt(0)
	s_barrier
	s_waitcnt lgkmcnt(0)
	v_mfma_f32_16x16x32_bf16 v[124:127], v[128:131], v[172:175], v[124:127]
	v_mfma_f32_16x16x32_bf16 v[120:123], v[136:139], v[172:175], v[120:123]
	v_mfma_f32_16x16x32_bf16 v[108:111], v[128:131], v[184:187], v[108:111]
	v_mfma_f32_16x16x32_bf16 v[104:107], v[136:139], v[184:187], v[104:107]
	v_mfma_f32_16x16x32_bf16 v[92:95], v[128:131], v[194:197], v[92:95]
	v_mfma_f32_16x16x32_bf16 v[88:91], v[136:139], v[194:197], v[88:91]
	v_mfma_f32_16x16x32_bf16 v[76:79], v[128:131], v[202:205], v[76:79]
	v_mfma_f32_16x16x32_bf16 v[72:75], v[136:139], v[202:205], v[72:75]
	v_mfma_f32_16x16x32_bf16 v[124:127], v[132:135], v[180:183], v[124:127]
	v_mfma_f32_16x16x32_bf16 v[120:123], v[140:143], v[180:183], v[120:123]
	v_mfma_f32_16x16x32_bf16 v[108:111], v[132:135], v[188:191], v[108:111]
	v_mfma_f32_16x16x32_bf16 v[104:107], v[140:143], v[188:191], v[104:107]
	v_mfma_f32_16x16x32_bf16 v[92:95], v[132:135], v[198:201], v[92:95]
	v_mfma_f32_16x16x32_bf16 v[88:91], v[140:143], v[198:201], v[88:91]
	v_mfma_f32_16x16x32_bf16 v[76:79], v[132:135], v[214:217], v[76:79]
	v_mfma_f32_16x16x32_bf16 v[72:75], v[140:143], v[214:217], v[72:75]
	v_mfma_f32_16x16x32_bf16 v[116:119], v[156:159], v[172:175], v[116:119]
	v_mfma_f32_16x16x32_bf16 v[112:115], v[164:167], v[172:175], v[112:115]
	v_mfma_f32_16x16x32_bf16 v[100:103], v[156:159], v[184:187], v[100:103]
	v_mfma_f32_16x16x32_bf16 v[96:99], v[164:167], v[184:187], v[96:99]
	v_mfma_f32_16x16x32_bf16 v[84:87], v[156:159], v[194:197], v[84:87]
	v_mfma_f32_16x16x32_bf16 v[80:83], v[164:167], v[194:197], v[80:83]
	v_mfma_f32_16x16x32_bf16 v[68:71], v[156:159], v[202:205], v[68:71]
	v_mfma_f32_16x16x32_bf16 v[64:67], v[164:167], v[202:205], v[64:67]
	v_mfma_f32_16x16x32_bf16 v[116:119], v[160:163], v[180:183], v[116:119]
	v_mfma_f32_16x16x32_bf16 v[112:115], v[168:171], v[180:183], v[112:115]
	v_mfma_f32_16x16x32_bf16 v[100:103], v[160:163], v[188:191], v[100:103]
	v_mfma_f32_16x16x32_bf16 v[96:99], v[168:171], v[188:191], v[96:99]
	v_mfma_f32_16x16x32_bf16 v[84:87], v[160:163], v[198:201], v[84:87]
	v_mfma_f32_16x16x32_bf16 v[80:83], v[168:171], v[198:201], v[80:83]
	v_mfma_f32_16x16x32_bf16 v[68:71], v[160:163], v[214:217], v[68:71]
	v_mfma_f32_16x16x32_bf16 v[64:67], v[168:171], v[214:217], v[64:67]
	s_barrier
	s_add_i32 s16, s40, s61
	v_lshl_add_u64 v[218:219], v[218:219], 0, s[76:77]
	s_mov_b32 m0, s16
	ds_read_b128 v[172:175], v179 offset:49152
	ds_read_b128 v[180:183], v179 offset:50176
	ds_read_b128 v[184:187], v179 offset:51200
	ds_read_b128 v[188:191], v179 offset:52224
	ds_read_b128 v[194:197], v179 offset:53248
	ds_read_b128 v[198:201], v179 offset:54272
	ds_read_b128 v[202:205], v179 offset:55296
	ds_read_b128 v[214:217], v179 offset:56320
	global_load_lds_dwordx4 v[218:219], off
	s_add_i32 m0, s16, 0x2000
	s_add_u32 s14, s14, 0x40080
	v_lshl_add_u64 v[218:219], v[220:221], 0, s[76:77]
	s_addc_u32 s15, s15, 0
	s_add_i32 s16, s44, s61
	global_load_lds_dwordx4 v[218:219], off
	v_lshl_add_u64 v[218:219], s[14:15], 0, v[148:149]
	s_mov_b32 m0, s16
	s_nop 0
	global_load_lds_dwordx4 v[218:219], off
	v_lshl_add_u64 v[218:219], s[14:15], 0, v[144:145]
	s_add_i32 m0, s16, 0x2000
	s_nop 0
	global_load_lds_dwordx4 v[218:219], off
	v_lshl_add_u64 v[218:219], v[222:223], 0, s[76:77]
	s_mov_b32 m0, s26
	s_nop 0
	global_load_lds_dwordx4 v[218:219], off
	v_lshl_add_u64 v[218:219], v[224:225], 0, s[76:77]
	s_mov_b32 m0, s27
	s_nop 0
	global_load_lds_dwordx4 v[218:219], off
	s_waitcnt vmcnt(8)
	s_waitcnt lgkmcnt(0)
	s_barrier
	s_waitcnt lgkmcnt(0)
	v_mfma_f32_16x16x32_bf16 v[60:63], v[128:131], v[172:175], v[60:63]
	v_mfma_f32_16x16x32_bf16 v[56:59], v[136:139], v[172:175], v[56:59]
	v_mfma_f32_16x16x32_bf16 v[44:47], v[128:131], v[184:187], v[44:47]
	v_mfma_f32_16x16x32_bf16 v[40:43], v[136:139], v[184:187], v[40:43]
	v_mfma_f32_16x16x32_bf16 v[28:31], v[128:131], v[194:197], v[28:31]
	v_mfma_f32_16x16x32_bf16 v[24:27], v[136:139], v[194:197], v[24:27]
	v_mfma_f32_16x16x32_bf16 v[12:15], v[128:131], v[202:205], v[12:15]
	v_mfma_f32_16x16x32_bf16 v[8:11], v[136:139], v[202:205], v[8:11]
	v_mfma_f32_16x16x32_bf16 v[60:63], v[132:135], v[180:183], v[60:63]
	v_mfma_f32_16x16x32_bf16 v[56:59], v[140:143], v[180:183], v[56:59]
	v_mfma_f32_16x16x32_bf16 v[44:47], v[132:135], v[188:191], v[44:47]
	v_mfma_f32_16x16x32_bf16 v[40:43], v[140:143], v[188:191], v[40:43]
	v_mfma_f32_16x16x32_bf16 v[28:31], v[132:135], v[198:201], v[28:31]
	v_mfma_f32_16x16x32_bf16 v[24:27], v[140:143], v[198:201], v[24:27]
	v_mfma_f32_16x16x32_bf16 v[12:15], v[132:135], v[214:217], v[12:15]
	v_mfma_f32_16x16x32_bf16 v[8:11], v[140:143], v[214:217], v[8:11]
	v_mfma_f32_16x16x32_bf16 v[52:55], v[156:159], v[172:175], v[52:55]
	v_mfma_f32_16x16x32_bf16 v[48:51], v[164:167], v[172:175], v[48:51]
	v_mfma_f32_16x16x32_bf16 v[36:39], v[156:159], v[184:187], v[36:39]
	v_mfma_f32_16x16x32_bf16 v[32:35], v[164:167], v[184:187], v[32:35]
	v_mfma_f32_16x16x32_bf16 v[20:23], v[156:159], v[194:197], v[20:23]
	v_mfma_f32_16x16x32_bf16 v[16:19], v[164:167], v[194:197], v[16:19]
	v_mfma_f32_16x16x32_bf16 v[4:7], v[156:159], v[202:205], v[4:7]
	v_mfma_f32_16x16x32_bf16 v[0:3], v[164:167], v[202:205], v[0:3]
	v_mfma_f32_16x16x32_bf16 v[52:55], v[160:163], v[180:183], v[52:55]
	v_mfma_f32_16x16x32_bf16 v[48:51], v[168:171], v[180:183], v[48:51]
	v_mfma_f32_16x16x32_bf16 v[36:39], v[160:163], v[188:191], v[36:39]
	v_mfma_f32_16x16x32_bf16 v[32:35], v[168:171], v[188:191], v[32:35]
	v_mfma_f32_16x16x32_bf16 v[20:23], v[160:163], v[198:201], v[20:23]
	v_mfma_f32_16x16x32_bf16 v[16:19], v[168:171], v[198:201], v[16:19]
	v_mfma_f32_16x16x32_bf16 v[4:7], v[160:163], v[214:217], v[4:7]
	v_mfma_f32_16x16x32_bf16 v[0:3], v[168:171], v[214:217], v[0:3]
	s_barrier
	s_add_i32 s39, s39, 2
	s_add_u32 s33, s33, 0x100
	s_addc_u32 s38, s38, 0
	s_add_u32 s12, s12, 0x100
	s_addc_u32 s13, s13, 0
	s_cmp_gt_u32 s39, 13
	s_cbranch_scc0 .LBB0_299
	s_and_b64 vcc, exec, s[80:81]
	s_cbranch_vccz .LBB0_302
	s_barrier

.LBB0_650:
	s_add_u32 s24, s22, 0x100
	s_addc_u32 s25, s23, 0
	s_add_u32 s26, s19, s22
	s_addc_u32 s27, s63, s23
	s_cmp_eq_u32 s64, 4
	s_cselect_b32 s28, 0, s24
	s_cselect_b32 s29, 0, s25
	s_cselect_b32 s26, s13, s26
	s_cselect_b32 s27, s11, s27
	s_add_u32 s28, s2, s28
	s_addc_u32 s29, s3, s29
	s_add_i32 s65, 0, 0x10000
	s_add_i32 s66, 0, 0x14000
	v_add_u32_e32 v140, s65, v166
	v_add_u32_e32 v172, s66, v166
	ds_read_b128 v[128:131], v140
	ds_read_b128 v[132:135], v140 offset:1024
	ds_read_b128 v[136:139], v140 offset:2048
	ds_read_b128 v[140:143], v140 offset:3072
	ds_read_b128 v[144:147], v172
	ds_read_b128 v[148:151], v172 offset:1024
	ds_read_b128 v[168:171], v172 offset:2048
	ds_read_b128 v[172:175], v172 offset:3072
	v_lshl_add_u64 v[218:219], v[162:163], 0, s[22:23]
	s_add_i32 m0, s21, 0xc000
	ds_read_b128 v[176:179], v167
	ds_read_b128 v[180:183], v167 offset:1024
	ds_read_b128 v[184:187], v167 offset:2048
	ds_read_b128 v[188:191], v167 offset:3072
	ds_read_b128 v[194:197], v167 offset:4096
	ds_read_b128 v[198:201], v167 offset:5120
	ds_read_b128 v[202:205], v167 offset:6144
	ds_read_b128 v[214:217], v167 offset:7168
	global_load_lds_dwordx4 v[218:219], off
	v_lshl_add_u64 v[218:219], v[160:161], 0, s[22:23]
	s_add_i32 m0, s21, 0xe000
	s_nop 0
	global_load_lds_dwordx4 v[218:219], off
	s_waitcnt vmcnt(8)
	s_waitcnt lgkmcnt(0)
	s_barrier
	s_waitcnt lgkmcnt(0)
	v_mfma_f32_16x16x32_bf16 v[124:127], v[128:131], v[176:179], v[124:127]
	v_mfma_f32_16x16x32_bf16 v[120:123], v[136:139], v[176:179], v[120:123]
	v_mfma_f32_16x16x32_bf16 v[108:111], v[128:131], v[184:187], v[108:111]
	v_mfma_f32_16x16x32_bf16 v[104:107], v[136:139], v[184:187], v[104:107]
	v_mfma_f32_16x16x32_bf16 v[96:99], v[128:131], v[194:197], v[96:99]
	v_mfma_f32_16x16x32_bf16 v[88:91], v[136:139], v[194:197], v[88:91]
	v_mfma_f32_16x16x32_bf16 v[80:83], v[128:131], v[202:205], v[80:83]
	v_mfma_f32_16x16x32_bf16 v[72:75], v[136:139], v[202:205], v[72:75]
	v_mfma_f32_16x16x32_bf16 v[124:127], v[132:135], v[180:183], v[124:127]
	v_mfma_f32_16x16x32_bf16 v[120:123], v[140:143], v[180:183], v[120:123]
	v_mfma_f32_16x16x32_bf16 v[108:111], v[132:135], v[188:191], v[108:111]
	v_mfma_f32_16x16x32_bf16 v[104:107], v[140:143], v[188:191], v[104:107]
	v_mfma_f32_16x16x32_bf16 v[96:99], v[132:135], v[198:201], v[96:99]
	v_mfma_f32_16x16x32_bf16 v[88:91], v[140:143], v[198:201], v[88:91]
	v_mfma_f32_16x16x32_bf16 v[80:83], v[132:135], v[214:217], v[80:83]
	v_mfma_f32_16x16x32_bf16 v[72:75], v[140:143], v[214:217], v[72:75]
	v_mfma_f32_16x16x32_bf16 v[116:119], v[144:147], v[176:179], v[116:119]
	v_mfma_f32_16x16x32_bf16 v[112:115], v[168:171], v[176:179], v[112:115]
	v_mfma_f32_16x16x32_bf16 v[100:103], v[144:147], v[184:187], v[100:103]
	v_mfma_f32_16x16x32_bf16 v[92:95], v[168:171], v[184:187], v[92:95]
	v_mfma_f32_16x16x32_bf16 v[84:87], v[144:147], v[194:197], v[84:87]
	v_mfma_f32_16x16x32_bf16 v[76:79], v[168:171], v[194:197], v[76:79]
	v_mfma_f32_16x16x32_bf16 v[68:71], v[144:147], v[202:205], v[68:71]
	v_mfma_f32_16x16x32_bf16 v[64:67], v[168:171], v[202:205], v[64:67]
	v_mfma_f32_16x16x32_bf16 v[116:119], v[148:151], v[180:183], v[116:119]
	v_mfma_f32_16x16x32_bf16 v[112:115], v[172:175], v[180:183], v[112:115]
	v_mfma_f32_16x16x32_bf16 v[100:103], v[148:151], v[188:191], v[100:103]
	v_mfma_f32_16x16x32_bf16 v[92:95], v[172:175], v[188:191], v[92:95]
	v_mfma_f32_16x16x32_bf16 v[84:87], v[148:151], v[198:201], v[84:87]
	v_mfma_f32_16x16x32_bf16 v[76:79], v[172:175], v[198:201], v[76:79]
	v_mfma_f32_16x16x32_bf16 v[68:71], v[148:151], v[214:217], v[68:71]
	v_mfma_f32_16x16x32_bf16 v[64:67], v[172:175], v[214:217], v[64:67]
	s_barrier
	s_add_i32 s22, s65, s35
	v_lshl_add_u64 v[218:219], s[26:27], 0, v[156:157]
	s_mov_b32 m0, s22
	ds_read_b128 v[176:179], v167 offset:16384
	ds_read_b128 v[180:183], v167 offset:17408
	ds_read_b128 v[184:187], v167 offset:18432
	ds_read_b128 v[188:191], v167 offset:19456
	ds_read_b128 v[194:197], v167 offset:20480
	ds_read_b128 v[198:201], v167 offset:21504
	ds_read_b128 v[202:205], v167 offset:22528
	ds_read_b128 v[214:217], v167 offset:23552
	global_load_lds_dwordx4 v[218:219], off
	s_add_i32 m0, s22, 0x2000
	s_add_u32 s22, s26, 0x20000
	v_lshl_add_u64 v[220:221], s[26:27], 0, v[152:153]
	s_addc_u32 s23, s27, 0
	s_add_i32 s65, s66, s35
	global_load_lds_dwordx4 v[220:221], off
	v_lshl_add_u64 v[222:223], s[22:23], 0, v[156:157]
	s_mov_b32 m0, s65
	v_lshl_add_u64 v[224:225], s[28:29], 0, v[154:155]
	global_load_lds_dwordx4 v[222:223], off
	v_lshl_add_u64 v[222:223], s[22:23], 0, v[152:153]
	s_add_i32 m0, s65, 0x2000
	s_nop 0
	global_load_lds_dwordx4 v[222:223], off
	v_lshl_add_u64 v[222:223], s[28:29], 0, v[158:159]
	s_mov_b32 m0, s21
	s_nop 0
	global_load_lds_dwordx4 v[222:223], off
	s_mov_b32 m0, s36
	s_nop 0
	global_load_lds_dwordx4 v[224:225], off
	s_waitcnt vmcnt(8)
	s_waitcnt lgkmcnt(0)
	s_barrier
	s_waitcnt lgkmcnt(0)
	v_mfma_f32_16x16x32_bf16 v[60:63], v[128:131], v[176:179], v[60:63]
	v_mfma_f32_16x16x32_bf16 v[56:59], v[136:139], v[176:179], v[56:59]
	v_mfma_f32_16x16x32_bf16 v[48:51], v[128:131], v[184:187], v[48:51]
	v_mfma_f32_16x16x32_bf16 v[40:43], v[136:139], v[184:187], v[40:43]
	v_mfma_f32_16x16x32_bf16 v[32:35], v[128:131], v[194:197], v[32:35]
	v_mfma_f32_16x16x32_bf16 v[24:27], v[136:139], v[194:197], v[24:27]
	v_mfma_f32_16x16x32_bf16 v[16:19], v[128:131], v[202:205], v[16:19]
	v_mfma_f32_16x16x32_bf16 v[8:11], v[136:139], v[202:205], v[8:11]
	v_mfma_f32_16x16x32_bf16 v[60:63], v[132:135], v[180:183], v[60:63]
	v_mfma_f32_16x16x32_bf16 v[56:59], v[140:143], v[180:183], v[56:59]
	v_mfma_f32_16x16x32_bf16 v[48:51], v[132:135], v[188:191], v[48:51]
	v_mfma_f32_16x16x32_bf16 v[40:43], v[140:143], v[188:191], v[40:43]
	v_mfma_f32_16x16x32_bf16 v[32:35], v[132:135], v[198:201], v[32:35]
	v_mfma_f32_16x16x32_bf16 v[24:27], v[140:143], v[198:201], v[24:27]
	v_mfma_f32_16x16x32_bf16 v[16:19], v[132:135], v[214:217], v[16:19]
	v_mfma_f32_16x16x32_bf16 v[8:11], v[140:143], v[214:217], v[8:11]
	v_mfma_f32_16x16x32_bf16 v[52:55], v[144:147], v[176:179], v[52:55]
	v_mfma_f32_16x16x32_bf16 v[44:47], v[168:171], v[176:179], v[44:47]
	v_mfma_f32_16x16x32_bf16 v[36:39], v[144:147], v[184:187], v[36:39]
	v_mfma_f32_16x16x32_bf16 v[28:31], v[168:171], v[184:187], v[28:31]
	v_mfma_f32_16x16x32_bf16 v[20:23], v[144:147], v[194:197], v[20:23]
	v_mfma_f32_16x16x32_bf16 v[12:15], v[168:171], v[194:197], v[12:15]
	v_mfma_f32_16x16x32_bf16 v[4:7], v[144:147], v[202:205], v[4:7]
	v_mfma_f32_16x16x32_bf16 v[0:3], v[168:171], v[202:205], v[0:3]
	v_mfma_f32_16x16x32_bf16 v[52:55], v[148:151], v[180:183], v[52:55]
	v_mfma_f32_16x16x32_bf16 v[44:47], v[172:175], v[180:183], v[44:47]
	v_mfma_f32_16x16x32_bf16 v[36:39], v[148:151], v[188:191], v[36:39]
	v_mfma_f32_16x16x32_bf16 v[28:31], v[172:175], v[188:191], v[28:31]
	v_mfma_f32_16x16x32_bf16 v[20:23], v[148:151], v[198:201], v[20:23]
	v_mfma_f32_16x16x32_bf16 v[12:15], v[172:175], v[198:201], v[12:15]
	v_mfma_f32_16x16x32_bf16 v[4:7], v[148:151], v[214:217], v[4:7]
	v_mfma_f32_16x16x32_bf16 v[0:3], v[172:175], v[214:217], v[0:3]
	s_barrier
	s_add_i32 s65, 0, 0x18000
	s_add_i32 s66, 0, 0x1c000
	v_add_u32_e32 v140, s65, v166
	v_add_u32_e32 v172, s66, v166
	ds_read_b128 v[128:131], v140
	ds_read_b128 v[132:135], v140 offset:1024
	ds_read_b128 v[136:139], v140 offset:2048
	ds_read_b128 v[140:143], v140 offset:3072
	ds_read_b128 v[144:147], v172
	ds_read_b128 v[148:151], v172 offset:1024
	ds_read_b128 v[168:171], v172 offset:2048
	ds_read_b128 v[172:175], v172 offset:3072
	s_add_u32 s22, s28, 0x20000
	s_addc_u32 s23, s29, 0
	s_mov_b32 m0, s37
	v_lshl_add_u64 v[226:227], s[22:23], 0, v[158:159]
	ds_read_b128 v[176:179], v167 offset:32768
	ds_read_b128 v[180:183], v167 offset:33792
	ds_read_b128 v[184:187], v167 offset:34816
	ds_read_b128 v[188:191], v167 offset:35840
	ds_read_b128 v[194:197], v167 offset:36864
	ds_read_b128 v[198:201], v167 offset:37888
	ds_read_b128 v[202:205], v167 offset:38912
	ds_read_b128 v[214:217], v167 offset:39936
	global_load_lds_dwordx4 v[226:227], off
	v_lshl_add_u64 v[226:227], s[22:23], 0, v[154:155]
	s_mov_b32 m0, s38
	s_nop 0
	global_load_lds_dwordx4 v[226:227], off
	s_waitcnt vmcnt(8)
	s_waitcnt lgkmcnt(0)
	s_barrier
	s_waitcnt lgkmcnt(0)
	v_mfma_f32_16x16x32_bf16 v[124:127], v[128:131], v[176:179], v[124:127]
	v_mfma_f32_16x16x32_bf16 v[120:123], v[136:139], v[176:179], v[120:123]
	v_mfma_f32_16x16x32_bf16 v[108:111], v[128:131], v[184:187], v[108:111]
	v_mfma_f32_16x16x32_bf16 v[104:107], v[136:139], v[184:187], v[104:107]
	v_mfma_f32_16x16x32_bf16 v[96:99], v[128:131], v[194:197], v[96:99]
	v_mfma_f32_16x16x32_bf16 v[88:91], v[136:139], v[194:197], v[88:91]
	v_mfma_f32_16x16x32_bf16 v[80:83], v[128:131], v[202:205], v[80:83]
	v_mfma_f32_16x16x32_bf16 v[72:75], v[136:139], v[202:205], v[72:75]
	v_mfma_f32_16x16x32_bf16 v[124:127], v[132:135], v[180:183], v[124:127]
	v_mfma_f32_16x16x32_bf16 v[120:123], v[140:143], v[180:183], v[120:123]
	v_mfma_f32_16x16x32_bf16 v[108:111], v[132:135], v[188:191], v[108:111]
	v_mfma_f32_16x16x32_bf16 v[104:107], v[140:143], v[188:191], v[104:107]
	v_mfma_f32_16x16x32_bf16 v[96:99], v[132:135], v[198:201], v[96:99]
	v_mfma_f32_16x16x32_bf16 v[88:91], v[140:143], v[198:201], v[88:91]
	v_mfma_f32_16x16x32_bf16 v[80:83], v[132:135], v[214:217], v[80:83]
	v_mfma_f32_16x16x32_bf16 v[72:75], v[140:143], v[214:217], v[72:75]
	v_mfma_f32_16x16x32_bf16 v[116:119], v[144:147], v[176:179], v[116:119]
	v_mfma_f32_16x16x32_bf16 v[112:115], v[168:171], v[176:179], v[112:115]
	v_mfma_f32_16x16x32_bf16 v[100:103], v[144:147], v[184:187], v[100:103]
	v_mfma_f32_16x16x32_bf16 v[92:95], v[168:171], v[184:187], v[92:95]
	v_mfma_f32_16x16x32_bf16 v[84:87], v[144:147], v[194:197], v[84:87]
	v_mfma_f32_16x16x32_bf16 v[76:79], v[168:171], v[194:197], v[76:79]
	v_mfma_f32_16x16x32_bf16 v[68:71], v[144:147], v[202:205], v[68:71]
	v_mfma_f32_16x16x32_bf16 v[64:67], v[168:171], v[202:205], v[64:67]
	v_mfma_f32_16x16x32_bf16 v[116:119], v[148:151], v[180:183], v[116:119]
	v_mfma_f32_16x16x32_bf16 v[112:115], v[172:175], v[180:183], v[112:115]
	v_mfma_f32_16x16x32_bf16 v[100:103], v[148:151], v[188:191], v[100:103]
	v_mfma_f32_16x16x32_bf16 v[92:95], v[172:175], v[188:191], v[92:95]
	v_mfma_f32_16x16x32_bf16 v[84:87], v[148:151], v[198:201], v[84:87]
	v_mfma_f32_16x16x32_bf16 v[76:79], v[172:175], v[198:201], v[76:79]
	v_mfma_f32_16x16x32_bf16 v[68:71], v[148:151], v[214:217], v[68:71]
	v_mfma_f32_16x16x32_bf16 v[64:67], v[172:175], v[214:217], v[64:67]
	s_barrier
	s_add_i32 s22, s65, s35
	v_lshl_add_u64 v[218:219], v[218:219], 0, s[76:77]
	s_mov_b32 m0, s22
	ds_read_b128 v[176:179], v167 offset:49152
	ds_read_b128 v[180:183], v167 offset:50176
	ds_read_b128 v[184:187], v167 offset:51200
	ds_read_b128 v[188:191], v167 offset:52224
	ds_read_b128 v[194:197], v167 offset:53248
	ds_read_b128 v[198:201], v167 offset:54272
	ds_read_b128 v[202:205], v167 offset:55296
	ds_read_b128 v[214:217], v167 offset:56320
	global_load_lds_dwordx4 v[218:219], off
	s_add_i32 m0, s22, 0x2000
	s_add_u32 s22, s26, 0x20080
	v_lshl_add_u64 v[218:219], v[220:221], 0, s[76:77]
	s_addc_u32 s23, s27, 0
	s_add_i32 s26, s66, s35
	global_load_lds_dwordx4 v[218:219], off
	v_lshl_add_u64 v[218:219], s[22:23], 0, v[156:157]
	s_mov_b32 m0, s26
	s_nop 0
	global_load_lds_dwordx4 v[218:219], off
	v_lshl_add_u64 v[218:219], s[22:23], 0, v[152:153]
	s_add_i32 m0, s26, 0x2000
	s_nop 0
	global_load_lds_dwordx4 v[218:219], off
	v_lshl_add_u64 v[218:219], v[222:223], 0, s[76:77]
	s_mov_b32 m0, s44
	s_nop 0
	global_load_lds_dwordx4 v[218:219], off
	v_lshl_add_u64 v[218:219], v[224:225], 0, s[76:77]
	s_mov_b32 m0, s45
	s_nop 0
	global_load_lds_dwordx4 v[218:219], off
	s_waitcnt vmcnt(8)
	s_waitcnt lgkmcnt(0)
	s_barrier
	s_waitcnt lgkmcnt(0)
	v_mfma_f32_16x16x32_bf16 v[60:63], v[128:131], v[176:179], v[60:63]
	v_mfma_f32_16x16x32_bf16 v[56:59], v[136:139], v[176:179], v[56:59]
	v_mfma_f32_16x16x32_bf16 v[48:51], v[128:131], v[184:187], v[48:51]
	v_mfma_f32_16x16x32_bf16 v[40:43], v[136:139], v[184:187], v[40:43]
	v_mfma_f32_16x16x32_bf16 v[32:35], v[128:131], v[194:197], v[32:35]
	v_mfma_f32_16x16x32_bf16 v[24:27], v[136:139], v[194:197], v[24:27]
	v_mfma_f32_16x16x32_bf16 v[16:19], v[128:131], v[202:205], v[16:19]
	v_mfma_f32_16x16x32_bf16 v[8:11], v[136:139], v[202:205], v[8:11]
	v_mfma_f32_16x16x32_bf16 v[60:63], v[132:135], v[180:183], v[60:63]
	v_mfma_f32_16x16x32_bf16 v[56:59], v[140:143], v[180:183], v[56:59]
	v_mfma_f32_16x16x32_bf16 v[48:51], v[132:135], v[188:191], v[48:51]
	v_mfma_f32_16x16x32_bf16 v[40:43], v[140:143], v[188:191], v[40:43]
	v_mfma_f32_16x16x32_bf16 v[32:35], v[132:135], v[198:201], v[32:35]
	v_mfma_f32_16x16x32_bf16 v[24:27], v[140:143], v[198:201], v[24:27]
	v_mfma_f32_16x16x32_bf16 v[16:19], v[132:135], v[214:217], v[16:19]
	v_mfma_f32_16x16x32_bf16 v[8:11], v[140:143], v[214:217], v[8:11]
	v_mfma_f32_16x16x32_bf16 v[52:55], v[144:147], v[176:179], v[52:55]
	v_mfma_f32_16x16x32_bf16 v[44:47], v[168:171], v[176:179], v[44:47]
	v_mfma_f32_16x16x32_bf16 v[36:39], v[144:147], v[184:187], v[36:39]
	v_mfma_f32_16x16x32_bf16 v[28:31], v[168:171], v[184:187], v[28:31]
	v_mfma_f32_16x16x32_bf16 v[20:23], v[144:147], v[194:197], v[20:23]
	v_mfma_f32_16x16x32_bf16 v[12:15], v[168:171], v[194:197], v[12:15]
	v_mfma_f32_16x16x32_bf16 v[4:7], v[144:147], v[202:205], v[4:7]
	v_mfma_f32_16x16x32_bf16 v[0:3], v[168:171], v[202:205], v[0:3]
	v_mfma_f32_16x16x32_bf16 v[52:55], v[148:151], v[180:183], v[52:55]
	v_mfma_f32_16x16x32_bf16 v[44:47], v[172:175], v[180:183], v[44:47]
	v_mfma_f32_16x16x32_bf16 v[36:39], v[148:151], v[188:191], v[36:39]
	v_mfma_f32_16x16x32_bf16 v[28:31], v[172:175], v[188:191], v[28:31]
	v_mfma_f32_16x16x32_bf16 v[20:23], v[148:151], v[198:201], v[20:23]
	v_mfma_f32_16x16x32_bf16 v[12:15], v[172:175], v[198:201], v[12:15]
	v_mfma_f32_16x16x32_bf16 v[4:7], v[148:151], v[214:217], v[4:7]
	v_mfma_f32_16x16x32_bf16 v[0:3], v[172:175], v[214:217], v[0:3]
	s_barrier
	s_add_i32 s64, s64, 2
	s_cmp_gt_u32 s64, 5
	s_mov_b64 s[22:23], s[24:25]
	s_cbranch_scc0 .LBB0_650
	s_and_b64 vcc, exec, s[8:9]
	s_cbranch_vccz .LBB0_653
	s_barrier

.LBB0_670:
	s_add_u32 s19, s24, 0xffe00080
	s_addc_u32 s26, s25, -1
	s_add_i32 s63, 0, 0x10000
	s_cmpk_eq_i32 s13, 0x7c
	s_cselect_b32 s29, s15, s26
	s_cselect_b32 s28, s14, s19
	s_cselect_b32 s27, s17, s11
	s_cselect_b32 s26, s16, s9
	s_add_i32 s19, 0, 0x14000
	v_add_u32_e32 v140, s63, v170
	v_add_u32_e32 v172, s19, v170
	ds_read_b128 v[128:131], v140
	ds_read_b128 v[132:135], v140 offset:1024
	ds_read_b128 v[136:139], v140 offset:2048
	ds_read_b128 v[140:143], v140 offset:3072
	ds_read_b128 v[144:147], v172
	ds_read_b128 v[148:151], v172 offset:1024
	ds_read_b128 v[152:155], v172 offset:2048
	ds_read_b128 v[172:175], v172 offset:3072
	v_lshl_add_u64 v[218:219], s[24:25], 0, v[166:167]
	s_add_i32 m0, s23, 0xc000
	ds_read_b128 v[176:179], v171
	ds_read_b128 v[180:183], v171 offset:1024
	ds_read_b128 v[184:187], v171 offset:2048
	ds_read_b128 v[188:191], v171 offset:3072
	ds_read_b128 v[194:197], v171 offset:4096
	ds_read_b128 v[198:201], v171 offset:5120
	ds_read_b128 v[202:205], v171 offset:6144
	ds_read_b128 v[214:217], v171 offset:7168
	global_load_lds_dwordx4 v[218:219], off
	v_lshl_add_u64 v[218:219], s[24:25], 0, v[164:165]
	s_add_i32 m0, s23, 0xe000
	s_nop 0
	global_load_lds_dwordx4 v[218:219], off
	s_waitcnt vmcnt(8)
	s_waitcnt lgkmcnt(0)
	s_barrier
	s_waitcnt lgkmcnt(0)
	v_mfma_f32_16x16x32_bf16 v[124:127], v[128:131], v[176:179], v[124:127]
	v_mfma_f32_16x16x32_bf16 v[120:123], v[136:139], v[176:179], v[120:123]
	v_mfma_f32_16x16x32_bf16 v[108:111], v[128:131], v[184:187], v[108:111]
	v_mfma_f32_16x16x32_bf16 v[104:107], v[136:139], v[184:187], v[104:107]
	v_mfma_f32_16x16x32_bf16 v[96:99], v[128:131], v[194:197], v[96:99]
	v_mfma_f32_16x16x32_bf16 v[88:91], v[136:139], v[194:197], v[88:91]
	v_mfma_f32_16x16x32_bf16 v[80:83], v[128:131], v[202:205], v[80:83]
	v_mfma_f32_16x16x32_bf16 v[72:75], v[136:139], v[202:205], v[72:75]
	v_mfma_f32_16x16x32_bf16 v[124:127], v[132:135], v[180:183], v[124:127]
	v_mfma_f32_16x16x32_bf16 v[120:123], v[140:143], v[180:183], v[120:123]
	v_mfma_f32_16x16x32_bf16 v[108:111], v[132:135], v[188:191], v[108:111]
	v_mfma_f32_16x16x32_bf16 v[104:107], v[140:143], v[188:191], v[104:107]
	v_mfma_f32_16x16x32_bf16 v[96:99], v[132:135], v[198:201], v[96:99]
	v_mfma_f32_16x16x32_bf16 v[88:91], v[140:143], v[198:201], v[88:91]
	v_mfma_f32_16x16x32_bf16 v[80:83], v[132:135], v[214:217], v[80:83]
	v_mfma_f32_16x16x32_bf16 v[72:75], v[140:143], v[214:217], v[72:75]
	v_mfma_f32_16x16x32_bf16 v[116:119], v[144:147], v[176:179], v[116:119]
	v_mfma_f32_16x16x32_bf16 v[112:115], v[152:155], v[176:179], v[112:115]
	v_mfma_f32_16x16x32_bf16 v[100:103], v[144:147], v[184:187], v[100:103]
	v_mfma_f32_16x16x32_bf16 v[92:95], v[152:155], v[184:187], v[92:95]
	v_mfma_f32_16x16x32_bf16 v[84:87], v[144:147], v[194:197], v[84:87]
	v_mfma_f32_16x16x32_bf16 v[76:79], v[152:155], v[194:197], v[76:79]
	v_mfma_f32_16x16x32_bf16 v[68:71], v[144:147], v[202:205], v[68:71]
	v_mfma_f32_16x16x32_bf16 v[64:67], v[152:155], v[202:205], v[64:67]
	v_mfma_f32_16x16x32_bf16 v[116:119], v[148:151], v[180:183], v[116:119]
	v_mfma_f32_16x16x32_bf16 v[112:115], v[172:175], v[180:183], v[112:115]
	v_mfma_f32_16x16x32_bf16 v[100:103], v[148:151], v[188:191], v[100:103]
	v_mfma_f32_16x16x32_bf16 v[92:95], v[172:175], v[188:191], v[92:95]
	v_mfma_f32_16x16x32_bf16 v[84:87], v[148:151], v[198:201], v[84:87]
	v_mfma_f32_16x16x32_bf16 v[76:79], v[172:175], v[198:201], v[76:79]
	v_mfma_f32_16x16x32_bf16 v[68:71], v[148:151], v[214:217], v[68:71]
	v_mfma_f32_16x16x32_bf16 v[64:67], v[172:175], v[214:217], v[64:67]
	s_barrier
	s_add_i32 s63, s63, s36
	v_lshl_add_u64 v[218:219], s[26:27], 0, v[160:161]
	s_mov_b32 m0, s63
	ds_read_b128 v[176:179], v171 offset:16384
	ds_read_b128 v[180:183], v171 offset:17408
	ds_read_b128 v[184:187], v171 offset:18432
	ds_read_b128 v[188:191], v171 offset:19456
	ds_read_b128 v[194:197], v171 offset:20480
	ds_read_b128 v[198:201], v171 offset:21504
	ds_read_b128 v[202:205], v171 offset:22528
	ds_read_b128 v[214:217], v171 offset:23552
	global_load_lds_dwordx4 v[218:219], off
	s_add_i32 m0, s63, 0x2000
	s_add_u32 s64, s26, 0x200000
	v_lshl_add_u64 v[220:221], s[26:27], 0, v[156:157]
	s_addc_u32 s65, s27, 0
	s_add_i32 s19, s19, s36
	global_load_lds_dwordx4 v[220:221], off
	v_lshl_add_u64 v[222:223], s[64:65], 0, v[160:161]
	s_mov_b32 m0, s19
	v_lshl_add_u64 v[224:225], s[28:29], 0, v[158:159]
	global_load_lds_dwordx4 v[222:223], off
	v_lshl_add_u64 v[222:223], s[64:65], 0, v[156:157]
	s_add_i32 m0, s19, 0x2000
	s_nop 0
	global_load_lds_dwordx4 v[222:223], off
	v_lshl_add_u64 v[222:223], s[28:29], 0, v[162:163]
	s_mov_b32 m0, s23
	s_nop 0
	global_load_lds_dwordx4 v[222:223], off
	s_mov_b32 m0, s21
	s_nop 0
	global_load_lds_dwordx4 v[224:225], off
	s_waitcnt vmcnt(8)
	s_waitcnt lgkmcnt(0)
	s_barrier
	s_waitcnt lgkmcnt(0)
	v_mfma_f32_16x16x32_bf16 v[60:63], v[128:131], v[176:179], v[60:63]
	v_mfma_f32_16x16x32_bf16 v[56:59], v[136:139], v[176:179], v[56:59]
	v_mfma_f32_16x16x32_bf16 v[48:51], v[128:131], v[184:187], v[48:51]
	v_mfma_f32_16x16x32_bf16 v[40:43], v[136:139], v[184:187], v[40:43]
	v_mfma_f32_16x16x32_bf16 v[32:35], v[128:131], v[194:197], v[32:35]
	v_mfma_f32_16x16x32_bf16 v[24:27], v[136:139], v[194:197], v[24:27]
	v_mfma_f32_16x16x32_bf16 v[16:19], v[128:131], v[202:205], v[16:19]
	v_mfma_f32_16x16x32_bf16 v[8:11], v[136:139], v[202:205], v[8:11]
	v_mfma_f32_16x16x32_bf16 v[60:63], v[132:135], v[180:183], v[60:63]
	v_mfma_f32_16x16x32_bf16 v[56:59], v[140:143], v[180:183], v[56:59]
	v_mfma_f32_16x16x32_bf16 v[48:51], v[132:135], v[188:191], v[48:51]
	v_mfma_f32_16x16x32_bf16 v[40:43], v[140:143], v[188:191], v[40:43]
	v_mfma_f32_16x16x32_bf16 v[32:35], v[132:135], v[198:201], v[32:35]
	v_mfma_f32_16x16x32_bf16 v[24:27], v[140:143], v[198:201], v[24:27]
	v_mfma_f32_16x16x32_bf16 v[16:19], v[132:135], v[214:217], v[16:19]
	v_mfma_f32_16x16x32_bf16 v[8:11], v[140:143], v[214:217], v[8:11]
	v_mfma_f32_16x16x32_bf16 v[52:55], v[144:147], v[176:179], v[52:55]
	v_mfma_f32_16x16x32_bf16 v[44:47], v[152:155], v[176:179], v[44:47]
	v_mfma_f32_16x16x32_bf16 v[36:39], v[144:147], v[184:187], v[36:39]
	v_mfma_f32_16x16x32_bf16 v[28:31], v[152:155], v[184:187], v[28:31]
	v_mfma_f32_16x16x32_bf16 v[20:23], v[144:147], v[194:197], v[20:23]
	v_mfma_f32_16x16x32_bf16 v[12:15], v[152:155], v[194:197], v[12:15]
	v_mfma_f32_16x16x32_bf16 v[4:7], v[144:147], v[202:205], v[4:7]
	v_mfma_f32_16x16x32_bf16 v[0:3], v[152:155], v[202:205], v[0:3]
	v_mfma_f32_16x16x32_bf16 v[52:55], v[148:151], v[180:183], v[52:55]
	v_mfma_f32_16x16x32_bf16 v[44:47], v[172:175], v[180:183], v[44:47]
	v_mfma_f32_16x16x32_bf16 v[36:39], v[148:151], v[188:191], v[36:39]
	v_mfma_f32_16x16x32_bf16 v[28:31], v[172:175], v[188:191], v[28:31]
	v_mfma_f32_16x16x32_bf16 v[20:23], v[148:151], v[198:201], v[20:23]
	v_mfma_f32_16x16x32_bf16 v[12:15], v[172:175], v[198:201], v[12:15]
	v_mfma_f32_16x16x32_bf16 v[4:7], v[148:151], v[214:217], v[4:7]
	v_mfma_f32_16x16x32_bf16 v[0:3], v[172:175], v[214:217], v[0:3]
	s_barrier
	s_add_i32 s19, 0, 0x18000
	s_add_i32 s63, 0, 0x1c000
	v_add_u32_e32 v140, s19, v170
	v_add_u32_e32 v172, s63, v170
	ds_read_b128 v[128:131], v140
	ds_read_b128 v[132:135], v140 offset:1024
	ds_read_b128 v[136:139], v140 offset:2048
	ds_read_b128 v[140:143], v140 offset:3072
	ds_read_b128 v[144:147], v172
	ds_read_b128 v[148:151], v172 offset:1024
	ds_read_b128 v[152:155], v172 offset:2048
	ds_read_b128 v[172:175], v172 offset:3072
	s_add_u32 s28, s28, 0x200000
	s_addc_u32 s29, s29, 0
	s_mov_b32 m0, s37
	v_lshl_add_u64 v[226:227], s[28:29], 0, v[162:163]
	ds_read_b128 v[176:179], v171 offset:32768
	ds_read_b128 v[180:183], v171 offset:33792
	ds_read_b128 v[184:187], v171 offset:34816
	ds_read_b128 v[188:191], v171 offset:35840
	ds_read_b128 v[194:197], v171 offset:36864
	ds_read_b128 v[198:201], v171 offset:37888
	ds_read_b128 v[202:205], v171 offset:38912
	ds_read_b128 v[214:217], v171 offset:39936
	global_load_lds_dwordx4 v[226:227], off
	v_lshl_add_u64 v[226:227], s[28:29], 0, v[158:159]
	s_mov_b32 m0, s38
	s_nop 0
	global_load_lds_dwordx4 v[226:227], off
	s_waitcnt vmcnt(8)
	s_waitcnt lgkmcnt(0)
	s_barrier
	s_waitcnt lgkmcnt(0)
	v_mfma_f32_16x16x32_bf16 v[124:127], v[128:131], v[176:179], v[124:127]
	v_mfma_f32_16x16x32_bf16 v[120:123], v[136:139], v[176:179], v[120:123]
	v_mfma_f32_16x16x32_bf16 v[108:111], v[128:131], v[184:187], v[108:111]
	v_mfma_f32_16x16x32_bf16 v[104:107], v[136:139], v[184:187], v[104:107]
	v_mfma_f32_16x16x32_bf16 v[96:99], v[128:131], v[194:197], v[96:99]
	v_mfma_f32_16x16x32_bf16 v[88:91], v[136:139], v[194:197], v[88:91]
	v_mfma_f32_16x16x32_bf16 v[80:83], v[128:131], v[202:205], v[80:83]
	v_mfma_f32_16x16x32_bf16 v[72:75], v[136:139], v[202:205], v[72:75]
	v_mfma_f32_16x16x32_bf16 v[124:127], v[132:135], v[180:183], v[124:127]
	v_mfma_f32_16x16x32_bf16 v[120:123], v[140:143], v[180:183], v[120:123]
	v_mfma_f32_16x16x32_bf16 v[108:111], v[132:135], v[188:191], v[108:111]
	v_mfma_f32_16x16x32_bf16 v[104:107], v[140:143], v[188:191], v[104:107]
	v_mfma_f32_16x16x32_bf16 v[96:99], v[132:135], v[198:201], v[96:99]
	v_mfma_f32_16x16x32_bf16 v[88:91], v[140:143], v[198:201], v[88:91]
	v_mfma_f32_16x16x32_bf16 v[80:83], v[132:135], v[214:217], v[80:83]
	v_mfma_f32_16x16x32_bf16 v[72:75], v[140:143], v[214:217], v[72:75]
	v_mfma_f32_16x16x32_bf16 v[116:119], v[144:147], v[176:179], v[116:119]
	v_mfma_f32_16x16x32_bf16 v[112:115], v[152:155], v[176:179], v[112:115]
	v_mfma_f32_16x16x32_bf16 v[100:103], v[144:147], v[184:187], v[100:103]
	v_mfma_f32_16x16x32_bf16 v[92:95], v[152:155], v[184:187], v[92:95]
	v_mfma_f32_16x16x32_bf16 v[84:87], v[144:147], v[194:197], v[84:87]
	v_mfma_f32_16x16x32_bf16 v[76:79], v[152:155], v[194:197], v[76:79]
	v_mfma_f32_16x16x32_bf16 v[68:71], v[144:147], v[202:205], v[68:71]
	v_mfma_f32_16x16x32_bf16 v[64:67], v[152:155], v[202:205], v[64:67]
	v_mfma_f32_16x16x32_bf16 v[116:119], v[148:151], v[180:183], v[116:119]
	v_mfma_f32_16x16x32_bf16 v[112:115], v[172:175], v[180:183], v[112:115]
	v_mfma_f32_16x16x32_bf16 v[100:103], v[148:151], v[188:191], v[100:103]
	v_mfma_f32_16x16x32_bf16 v[92:95], v[172:175], v[188:191], v[92:95]
	v_mfma_f32_16x16x32_bf16 v[84:87], v[148:151], v[198:201], v[84:87]
	v_mfma_f32_16x16x32_bf16 v[76:79], v[172:175], v[198:201], v[76:79]
	v_mfma_f32_16x16x32_bf16 v[68:71], v[148:151], v[214:217], v[68:71]
	v_mfma_f32_16x16x32_bf16 v[64:67], v[172:175], v[214:217], v[64:67]
	s_barrier
	s_add_i32 s19, s19, s36
	v_lshl_add_u64 v[218:219], v[218:219], 0, s[76:77]
	s_mov_b32 m0, s19
	ds_read_b128 v[176:179], v171 offset:49152
	ds_read_b128 v[180:183], v171 offset:50176
	ds_read_b128 v[184:187], v171 offset:51200
	ds_read_b128 v[188:191], v171 offset:52224
	ds_read_b128 v[194:197], v171 offset:53248
	ds_read_b128 v[198:201], v171 offset:54272
	ds_read_b128 v[202:205], v171 offset:55296
	ds_read_b128 v[214:217], v171 offset:56320
	global_load_lds_dwordx4 v[218:219], off
	s_add_i32 m0, s19, 0x2000
	s_add_u32 s26, s26, 0x200080
	v_lshl_add_u64 v[218:219], v[220:221], 0, s[76:77]
	s_addc_u32 s27, s27, 0
	s_add_i32 s19, s63, s36
	global_load_lds_dwordx4 v[218:219], off
	v_lshl_add_u64 v[218:219], s[26:27], 0, v[160:161]
	s_mov_b32 m0, s19
	s_nop 0
	global_load_lds_dwordx4 v[218:219], off
	v_lshl_add_u64 v[218:219], s[26:27], 0, v[156:157]
	s_add_i32 m0, s19, 0x2000
	s_nop 0
	global_load_lds_dwordx4 v[218:219], off
	v_lshl_add_u64 v[218:219], v[222:223], 0, s[76:77]
	s_mov_b32 m0, s44
	s_nop 0
	global_load_lds_dwordx4 v[218:219], off
	v_lshl_add_u64 v[218:219], v[224:225], 0, s[76:77]
	s_mov_b32 m0, s45
	s_nop 0
	global_load_lds_dwordx4 v[218:219], off
	s_waitcnt vmcnt(8)
	s_waitcnt lgkmcnt(0)
	s_barrier
	s_waitcnt lgkmcnt(0)
	v_mfma_f32_16x16x32_bf16 v[60:63], v[128:131], v[176:179], v[60:63]
	v_mfma_f32_16x16x32_bf16 v[56:59], v[136:139], v[176:179], v[56:59]
	v_mfma_f32_16x16x32_bf16 v[48:51], v[128:131], v[184:187], v[48:51]
	v_mfma_f32_16x16x32_bf16 v[40:43], v[136:139], v[184:187], v[40:43]
	v_mfma_f32_16x16x32_bf16 v[32:35], v[128:131], v[194:197], v[32:35]
	v_mfma_f32_16x16x32_bf16 v[24:27], v[136:139], v[194:197], v[24:27]
	v_mfma_f32_16x16x32_bf16 v[16:19], v[128:131], v[202:205], v[16:19]
	v_mfma_f32_16x16x32_bf16 v[8:11], v[136:139], v[202:205], v[8:11]
	v_mfma_f32_16x16x32_bf16 v[60:63], v[132:135], v[180:183], v[60:63]
	v_mfma_f32_16x16x32_bf16 v[56:59], v[140:143], v[180:183], v[56:59]
	v_mfma_f32_16x16x32_bf16 v[48:51], v[132:135], v[188:191], v[48:51]
	v_mfma_f32_16x16x32_bf16 v[40:43], v[140:143], v[188:191], v[40:43]
	v_mfma_f32_16x16x32_bf16 v[32:35], v[132:135], v[198:201], v[32:35]
	v_mfma_f32_16x16x32_bf16 v[24:27], v[140:143], v[198:201], v[24:27]
	v_mfma_f32_16x16x32_bf16 v[16:19], v[132:135], v[214:217], v[16:19]
	v_mfma_f32_16x16x32_bf16 v[8:11], v[140:143], v[214:217], v[8:11]
	v_mfma_f32_16x16x32_bf16 v[52:55], v[144:147], v[176:179], v[52:55]
	v_mfma_f32_16x16x32_bf16 v[44:47], v[152:155], v[176:179], v[44:47]
	v_mfma_f32_16x16x32_bf16 v[36:39], v[144:147], v[184:187], v[36:39]
	v_mfma_f32_16x16x32_bf16 v[28:31], v[152:155], v[184:187], v[28:31]
	v_mfma_f32_16x16x32_bf16 v[20:23], v[144:147], v[194:197], v[20:23]
	v_mfma_f32_16x16x32_bf16 v[12:15], v[152:155], v[194:197], v[12:15]
	v_mfma_f32_16x16x32_bf16 v[4:7], v[144:147], v[202:205], v[4:7]
	v_mfma_f32_16x16x32_bf16 v[0:3], v[152:155], v[202:205], v[0:3]
	v_mfma_f32_16x16x32_bf16 v[52:55], v[148:151], v[180:183], v[52:55]
	v_mfma_f32_16x16x32_bf16 v[44:47], v[172:175], v[180:183], v[44:47]
	v_mfma_f32_16x16x32_bf16 v[36:39], v[148:151], v[188:191], v[36:39]
	v_mfma_f32_16x16x32_bf16 v[28:31], v[172:175], v[188:191], v[28:31]
	v_mfma_f32_16x16x32_bf16 v[20:23], v[148:151], v[198:201], v[20:23]
	v_mfma_f32_16x16x32_bf16 v[12:15], v[172:175], v[198:201], v[12:15]
	v_mfma_f32_16x16x32_bf16 v[4:7], v[148:151], v[214:217], v[4:7]
	v_mfma_f32_16x16x32_bf16 v[0:3], v[172:175], v[214:217], v[0:3]
	s_barrier
	s_add_i32 s13, s13, 2
	s_add_u32 s9, s9, 0x100
	s_addc_u32 s11, s11, 0
	s_add_u32 s24, s24, 0x100
	s_addc_u32 s25, s25, 0
	s_cmpk_gt_u32 s13, 0x7d
	s_cbranch_scc0 .LBB0_670
	s_and_b64 vcc, exec, s[4:5]
	s_cbranch_vccz .LBB0_673
	s_barrier

.LBB0_1021:
	s_add_i32 s64, s63, 2
	s_add_u32 s14, s12, 0x100
	s_addc_u32 s15, s13, 0
	s_add_i32 s65, 0, 0x10000
	s_cmp_eq_u32 s63, 38
	s_cselect_b32 s19, s9, s15
	s_cselect_b32 s18, s8, s14
	s_cselect_b32 s17, s11, s61
	s_cselect_b32 s16, s10, s60
	s_add_i32 s66, 0, 0x14000
	v_add_u32_e32 v140, s65, v222
	v_add_u32_e32 v156, s66, v222
	ds_read_b128 v[128:131], v140
	ds_read_b128 v[132:135], v140 offset:1024
	ds_read_b128 v[136:139], v140 offset:2048
	ds_read_b128 v[140:143], v140 offset:3072
	ds_read_b128 v[144:147], v156
	ds_read_b128 v[148:151], v156 offset:1024
	ds_read_b128 v[152:155], v156 offset:2048
	ds_read_b128 v[156:159], v156 offset:3072
	v_lshl_add_u64 v[228:229], s[12:13], 0, v[204:205]
	s_add_i32 m0, s26, 0xc000
	ds_read_b128 v[160:163], v225
	ds_read_b128 v[164:167], v225 offset:1024
	ds_read_b128 v[168:171], v225 offset:2048
	ds_read_b128 v[172:175], v225 offset:3072
	ds_read_b128 v[176:179], v225 offset:4096
	ds_read_b128 v[180:183], v225 offset:5120
	ds_read_b128 v[184:187], v225 offset:6144
	ds_read_b128 v[188:191], v225 offset:7168
	global_load_lds_dwordx4 v[228:229], off
	v_lshl_add_u64 v[228:229], s[12:13], 0, v[202:203]
	s_add_i32 m0, s26, 0xe000
	s_nop 0
	global_load_lds_dwordx4 v[228:229], off
	s_waitcnt vmcnt(8)
	s_waitcnt lgkmcnt(0)
	s_barrier
	s_waitcnt lgkmcnt(0)
	v_mfma_f32_16x16x32_bf16 v[124:127], v[128:131], v[160:163], v[124:127]
	v_mfma_f32_16x16x32_bf16 v[120:123], v[136:139], v[160:163], v[120:123]
	v_mfma_f32_16x16x32_bf16 v[108:111], v[128:131], v[168:171], v[108:111]
	v_mfma_f32_16x16x32_bf16 v[104:107], v[136:139], v[168:171], v[104:107]
	v_mfma_f32_16x16x32_bf16 v[92:95], v[128:131], v[176:179], v[92:95]
	v_mfma_f32_16x16x32_bf16 v[88:91], v[136:139], v[176:179], v[88:91]
	v_mfma_f32_16x16x32_bf16 v[76:79], v[128:131], v[184:187], v[76:79]
	v_mfma_f32_16x16x32_bf16 v[72:75], v[136:139], v[184:187], v[72:75]
	v_mfma_f32_16x16x32_bf16 v[124:127], v[132:135], v[164:167], v[124:127]
	v_mfma_f32_16x16x32_bf16 v[120:123], v[140:143], v[164:167], v[120:123]
	v_mfma_f32_16x16x32_bf16 v[108:111], v[132:135], v[172:175], v[108:111]
	v_mfma_f32_16x16x32_bf16 v[104:107], v[140:143], v[172:175], v[104:107]
	v_mfma_f32_16x16x32_bf16 v[92:95], v[132:135], v[180:183], v[92:95]
	v_mfma_f32_16x16x32_bf16 v[88:91], v[140:143], v[180:183], v[88:91]
	v_mfma_f32_16x16x32_bf16 v[76:79], v[132:135], v[188:191], v[76:79]
	v_mfma_f32_16x16x32_bf16 v[72:75], v[140:143], v[188:191], v[72:75]
	v_mfma_f32_16x16x32_bf16 v[116:119], v[144:147], v[160:163], v[116:119]
	v_mfma_f32_16x16x32_bf16 v[112:115], v[152:155], v[160:163], v[112:115]
	v_mfma_f32_16x16x32_bf16 v[100:103], v[144:147], v[168:171], v[100:103]
	v_mfma_f32_16x16x32_bf16 v[96:99], v[152:155], v[168:171], v[96:99]
	v_mfma_f32_16x16x32_bf16 v[84:87], v[144:147], v[176:179], v[84:87]
	v_mfma_f32_16x16x32_bf16 v[80:83], v[152:155], v[176:179], v[80:83]
	v_mfma_f32_16x16x32_bf16 v[68:71], v[144:147], v[184:187], v[68:71]
	v_mfma_f32_16x16x32_bf16 v[64:67], v[152:155], v[184:187], v[64:67]
	v_mfma_f32_16x16x32_bf16 v[116:119], v[148:151], v[164:167], v[116:119]
	v_mfma_f32_16x16x32_bf16 v[112:115], v[156:159], v[164:167], v[112:115]
	v_mfma_f32_16x16x32_bf16 v[100:103], v[148:151], v[172:175], v[100:103]
	v_mfma_f32_16x16x32_bf16 v[96:99], v[156:159], v[172:175], v[96:99]
	v_mfma_f32_16x16x32_bf16 v[84:87], v[148:151], v[180:183], v[84:87]
	v_mfma_f32_16x16x32_bf16 v[80:83], v[156:159], v[180:183], v[80:83]
	v_mfma_f32_16x16x32_bf16 v[68:71], v[148:151], v[188:191], v[68:71]
	v_mfma_f32_16x16x32_bf16 v[64:67], v[156:159], v[188:191], v[64:67]
	s_barrier
	s_add_i32 s12, s65, s25
	v_lshl_add_u64 v[228:229], s[16:17], 0, v[196:197]
	s_mov_b32 m0, s12
	ds_read_b128 v[160:163], v225 offset:16384
	ds_read_b128 v[164:167], v225 offset:17408
	ds_read_b128 v[168:171], v225 offset:18432
	ds_read_b128 v[172:175], v225 offset:19456
	ds_read_b128 v[176:179], v225 offset:20480
	ds_read_b128 v[180:183], v225 offset:21504
	ds_read_b128 v[184:187], v225 offset:22528
	ds_read_b128 v[188:191], v225 offset:23552
	global_load_lds_dwordx4 v[228:229], off
	s_add_i32 m0, s12, 0x2000
	s_add_u32 s12, s16, 0xa0000
	v_lshl_add_u64 v[230:231], s[16:17], 0, v[200:201]
	s_addc_u32 s13, s17, 0
	s_add_i32 s65, s66, s25
	global_load_lds_dwordx4 v[230:231], off
	v_lshl_add_u64 v[232:233], s[12:13], 0, v[196:197]
	s_mov_b32 m0, s65
	v_lshl_add_u64 v[234:235], s[18:19], 0, v[198:199]
	global_load_lds_dwordx4 v[232:233], off
	v_lshl_add_u64 v[232:233], s[12:13], 0, v[200:201]
	s_add_i32 m0, s65, 0x2000
	s_nop 0
	global_load_lds_dwordx4 v[232:233], off
	v_lshl_add_u64 v[232:233], s[18:19], 0, v[194:195]
	s_mov_b32 m0, s26
	s_nop 0
	global_load_lds_dwordx4 v[232:233], off
	s_mov_b32 m0, s27
	s_nop 0
	global_load_lds_dwordx4 v[234:235], off
	s_waitcnt vmcnt(8)
	s_waitcnt lgkmcnt(0)
	s_barrier
	s_waitcnt lgkmcnt(0)
	v_mfma_f32_16x16x32_bf16 v[60:63], v[128:131], v[160:163], v[60:63]
	v_mfma_f32_16x16x32_bf16 v[56:59], v[136:139], v[160:163], v[56:59]
	v_mfma_f32_16x16x32_bf16 v[44:47], v[128:131], v[168:171], v[44:47]
	v_mfma_f32_16x16x32_bf16 v[40:43], v[136:139], v[168:171], v[40:43]
	v_mfma_f32_16x16x32_bf16 v[28:31], v[128:131], v[176:179], v[28:31]
	v_mfma_f32_16x16x32_bf16 v[24:27], v[136:139], v[176:179], v[24:27]
	v_mfma_f32_16x16x32_bf16 v[12:15], v[128:131], v[184:187], v[12:15]
	v_mfma_f32_16x16x32_bf16 v[8:11], v[136:139], v[184:187], v[8:11]
	v_mfma_f32_16x16x32_bf16 v[60:63], v[132:135], v[164:167], v[60:63]
	v_mfma_f32_16x16x32_bf16 v[56:59], v[140:143], v[164:167], v[56:59]
	v_mfma_f32_16x16x32_bf16 v[44:47], v[132:135], v[172:175], v[44:47]
	v_mfma_f32_16x16x32_bf16 v[40:43], v[140:143], v[172:175], v[40:43]
	v_mfma_f32_16x16x32_bf16 v[28:31], v[132:135], v[180:183], v[28:31]
	v_mfma_f32_16x16x32_bf16 v[24:27], v[140:143], v[180:183], v[24:27]
	v_mfma_f32_16x16x32_bf16 v[12:15], v[132:135], v[188:191], v[12:15]
	v_mfma_f32_16x16x32_bf16 v[8:11], v[140:143], v[188:191], v[8:11]
	v_mfma_f32_16x16x32_bf16 v[52:55], v[144:147], v[160:163], v[52:55]
	v_mfma_f32_16x16x32_bf16 v[48:51], v[152:155], v[160:163], v[48:51]
	v_mfma_f32_16x16x32_bf16 v[36:39], v[144:147], v[168:171], v[36:39]
	v_mfma_f32_16x16x32_bf16 v[32:35], v[152:155], v[168:171], v[32:35]
	v_mfma_f32_16x16x32_bf16 v[20:23], v[144:147], v[176:179], v[20:23]
	v_mfma_f32_16x16x32_bf16 v[16:19], v[152:155], v[176:179], v[16:19]
	v_mfma_f32_16x16x32_bf16 v[4:7], v[144:147], v[184:187], v[4:7]
	v_mfma_f32_16x16x32_bf16 v[0:3], v[152:155], v[184:187], v[0:3]
	v_mfma_f32_16x16x32_bf16 v[52:55], v[148:151], v[164:167], v[52:55]
	v_mfma_f32_16x16x32_bf16 v[48:51], v[156:159], v[164:167], v[48:51]
	v_mfma_f32_16x16x32_bf16 v[36:39], v[148:151], v[172:175], v[36:39]
	v_mfma_f32_16x16x32_bf16 v[32:35], v[156:159], v[172:175], v[32:35]
	v_mfma_f32_16x16x32_bf16 v[20:23], v[148:151], v[180:183], v[20:23]
	v_mfma_f32_16x16x32_bf16 v[16:19], v[156:159], v[180:183], v[16:19]
	v_mfma_f32_16x16x32_bf16 v[4:7], v[148:151], v[188:191], v[4:7]
	v_mfma_f32_16x16x32_bf16 v[0:3], v[156:159], v[188:191], v[0:3]
	s_barrier
	s_add_i32 s65, 0, 0x18000
	s_add_i32 s66, 0, 0x1c000
	v_add_u32_e32 v140, s65, v222
	v_add_u32_e32 v156, s66, v222
	ds_read_b128 v[128:131], v140
	ds_read_b128 v[132:135], v140 offset:1024
	ds_read_b128 v[136:139], v140 offset:2048
	ds_read_b128 v[140:143], v140 offset:3072
	ds_read_b128 v[144:147], v156
	ds_read_b128 v[148:151], v156 offset:1024
	ds_read_b128 v[152:155], v156 offset:2048
	ds_read_b128 v[156:159], v156 offset:3072
	s_add_u32 s12, s18, 0xa0000
	s_addc_u32 s13, s19, 0
	s_mov_b32 m0, s28
	v_lshl_add_u64 v[236:237], s[12:13], 0, v[194:195]
	ds_read_b128 v[160:163], v225 offset:32768
	ds_read_b128 v[164:167], v225 offset:33792
	ds_read_b128 v[168:171], v225 offset:34816
	ds_read_b128 v[172:175], v225 offset:35840
	ds_read_b128 v[176:179], v225 offset:36864
	ds_read_b128 v[180:183], v225 offset:37888
	ds_read_b128 v[184:187], v225 offset:38912
	ds_read_b128 v[188:191], v225 offset:39936
	global_load_lds_dwordx4 v[236:237], off
	v_lshl_add_u64 v[236:237], s[12:13], 0, v[198:199]
	s_mov_b32 m0, s29
	s_nop 0
	global_load_lds_dwordx4 v[236:237], off
	s_waitcnt vmcnt(8)
	s_waitcnt lgkmcnt(0)
	s_barrier
	s_waitcnt lgkmcnt(0)
	v_mfma_f32_16x16x32_bf16 v[124:127], v[128:131], v[160:163], v[124:127]
	v_mfma_f32_16x16x32_bf16 v[120:123], v[136:139], v[160:163], v[120:123]
	v_mfma_f32_16x16x32_bf16 v[108:111], v[128:131], v[168:171], v[108:111]
	v_mfma_f32_16x16x32_bf16 v[104:107], v[136:139], v[168:171], v[104:107]
	v_mfma_f32_16x16x32_bf16 v[92:95], v[128:131], v[176:179], v[92:95]
	v_mfma_f32_16x16x32_bf16 v[88:91], v[136:139], v[176:179], v[88:91]
	v_mfma_f32_16x16x32_bf16 v[76:79], v[128:131], v[184:187], v[76:79]
	v_mfma_f32_16x16x32_bf16 v[72:75], v[136:139], v[184:187], v[72:75]
	v_mfma_f32_16x16x32_bf16 v[124:127], v[132:135], v[164:167], v[124:127]
	v_mfma_f32_16x16x32_bf16 v[120:123], v[140:143], v[164:167], v[120:123]
	v_mfma_f32_16x16x32_bf16 v[108:111], v[132:135], v[172:175], v[108:111]
	v_mfma_f32_16x16x32_bf16 v[104:107], v[140:143], v[172:175], v[104:107]
	v_mfma_f32_16x16x32_bf16 v[92:95], v[132:135], v[180:183], v[92:95]
	v_mfma_f32_16x16x32_bf16 v[88:91], v[140:143], v[180:183], v[88:91]
	v_mfma_f32_16x16x32_bf16 v[76:79], v[132:135], v[188:191], v[76:79]
	v_mfma_f32_16x16x32_bf16 v[72:75], v[140:143], v[188:191], v[72:75]
	v_mfma_f32_16x16x32_bf16 v[116:119], v[144:147], v[160:163], v[116:119]
	v_mfma_f32_16x16x32_bf16 v[112:115], v[152:155], v[160:163], v[112:115]
	v_mfma_f32_16x16x32_bf16 v[100:103], v[144:147], v[168:171], v[100:103]
	v_mfma_f32_16x16x32_bf16 v[96:99], v[152:155], v[168:171], v[96:99]
	v_mfma_f32_16x16x32_bf16 v[84:87], v[144:147], v[176:179], v[84:87]
	v_mfma_f32_16x16x32_bf16 v[80:83], v[152:155], v[176:179], v[80:83]
	v_mfma_f32_16x16x32_bf16 v[68:71], v[144:147], v[184:187], v[68:71]
	v_mfma_f32_16x16x32_bf16 v[64:67], v[152:155], v[184:187], v[64:67]
	v_mfma_f32_16x16x32_bf16 v[116:119], v[148:151], v[164:167], v[116:119]
	v_mfma_f32_16x16x32_bf16 v[112:115], v[156:159], v[164:167], v[112:115]
	v_mfma_f32_16x16x32_bf16 v[100:103], v[148:151], v[172:175], v[100:103]
	v_mfma_f32_16x16x32_bf16 v[96:99], v[156:159], v[172:175], v[96:99]
	v_mfma_f32_16x16x32_bf16 v[84:87], v[148:151], v[180:183], v[84:87]
	v_mfma_f32_16x16x32_bf16 v[80:83], v[156:159], v[180:183], v[80:83]
	v_mfma_f32_16x16x32_bf16 v[68:71], v[148:151], v[188:191], v[68:71]
	v_mfma_f32_16x16x32_bf16 v[64:67], v[156:159], v[188:191], v[64:67]
	s_barrier
	s_add_i32 s12, s65, s25
	v_lshl_add_u64 v[228:229], v[228:229], 0, s[76:77]
	s_mov_b32 m0, s12
	ds_read_b128 v[160:163], v225 offset:49152
	ds_read_b128 v[164:167], v225 offset:50176
	ds_read_b128 v[168:171], v225 offset:51200
	ds_read_b128 v[172:175], v225 offset:52224
	ds_read_b128 v[176:179], v225 offset:53248
	ds_read_b128 v[180:183], v225 offset:54272
	ds_read_b128 v[184:187], v225 offset:55296
	ds_read_b128 v[188:191], v225 offset:56320
	global_load_lds_dwordx4 v[228:229], off
	s_add_i32 m0, s12, 0x2000
	s_add_u32 s12, s16, 0xa0080
	v_lshl_add_u64 v[228:229], v[230:231], 0, s[76:77]
	s_addc_u32 s13, s17, 0
	s_add_i32 s16, s66, s25
	global_load_lds_dwordx4 v[228:229], off
	v_lshl_add_u64 v[228:229], s[12:13], 0, v[196:197]
	s_mov_b32 m0, s16
	s_nop 0
	global_load_lds_dwordx4 v[228:229], off
	v_lshl_add_u64 v[228:229], s[12:13], 0, v[200:201]
	s_add_i32 m0, s16, 0x2000
	s_nop 0
	global_load_lds_dwordx4 v[228:229], off
	v_lshl_add_u64 v[228:229], v[232:233], 0, s[76:77]
	s_mov_b32 m0, s36
	s_nop 0
	global_load_lds_dwordx4 v[228:229], off
	v_lshl_add_u64 v[228:229], v[234:235], 0, s[76:77]
	s_mov_b32 m0, s37
	s_nop 0
	global_load_lds_dwordx4 v[228:229], off
	s_waitcnt vmcnt(8)
	s_waitcnt lgkmcnt(0)
	s_barrier
	s_waitcnt lgkmcnt(0)
	v_mfma_f32_16x16x32_bf16 v[60:63], v[128:131], v[160:163], v[60:63]
	v_mfma_f32_16x16x32_bf16 v[56:59], v[136:139], v[160:163], v[56:59]
	v_mfma_f32_16x16x32_bf16 v[44:47], v[128:131], v[168:171], v[44:47]
	v_mfma_f32_16x16x32_bf16 v[40:43], v[136:139], v[168:171], v[40:43]
	v_mfma_f32_16x16x32_bf16 v[28:31], v[128:131], v[176:179], v[28:31]
	v_mfma_f32_16x16x32_bf16 v[24:27], v[136:139], v[176:179], v[24:27]
	v_mfma_f32_16x16x32_bf16 v[12:15], v[128:131], v[184:187], v[12:15]
	v_mfma_f32_16x16x32_bf16 v[8:11], v[136:139], v[184:187], v[8:11]
	v_mfma_f32_16x16x32_bf16 v[60:63], v[132:135], v[164:167], v[60:63]
	v_mfma_f32_16x16x32_bf16 v[56:59], v[140:143], v[164:167], v[56:59]
	v_mfma_f32_16x16x32_bf16 v[44:47], v[132:135], v[172:175], v[44:47]
	v_mfma_f32_16x16x32_bf16 v[40:43], v[140:143], v[172:175], v[40:43]
	v_mfma_f32_16x16x32_bf16 v[28:31], v[132:135], v[180:183], v[28:31]
	v_mfma_f32_16x16x32_bf16 v[24:27], v[140:143], v[180:183], v[24:27]
	v_mfma_f32_16x16x32_bf16 v[12:15], v[132:135], v[188:191], v[12:15]
	v_mfma_f32_16x16x32_bf16 v[8:11], v[140:143], v[188:191], v[8:11]
	v_mfma_f32_16x16x32_bf16 v[52:55], v[144:147], v[160:163], v[52:55]
	v_mfma_f32_16x16x32_bf16 v[48:51], v[152:155], v[160:163], v[48:51]
	v_mfma_f32_16x16x32_bf16 v[36:39], v[144:147], v[168:171], v[36:39]
	v_mfma_f32_16x16x32_bf16 v[32:35], v[152:155], v[168:171], v[32:35]
	v_mfma_f32_16x16x32_bf16 v[20:23], v[144:147], v[176:179], v[20:23]
	v_mfma_f32_16x16x32_bf16 v[16:19], v[152:155], v[176:179], v[16:19]
	v_mfma_f32_16x16x32_bf16 v[4:7], v[144:147], v[184:187], v[4:7]
	v_mfma_f32_16x16x32_bf16 v[0:3], v[152:155], v[184:187], v[0:3]
	v_mfma_f32_16x16x32_bf16 v[52:55], v[148:151], v[164:167], v[52:55]
	v_mfma_f32_16x16x32_bf16 v[48:51], v[156:159], v[164:167], v[48:51]
	v_mfma_f32_16x16x32_bf16 v[36:39], v[148:151], v[172:175], v[36:39]
	v_mfma_f32_16x16x32_bf16 v[32:35], v[156:159], v[172:175], v[32:35]
	v_mfma_f32_16x16x32_bf16 v[20:23], v[148:151], v[180:183], v[20:23]
	v_mfma_f32_16x16x32_bf16 v[16:19], v[156:159], v[180:183], v[16:19]
	v_mfma_f32_16x16x32_bf16 v[4:7], v[148:151], v[188:191], v[4:7]
	v_mfma_f32_16x16x32_bf16 v[0:3], v[156:159], v[188:191], v[0:3]
	s_barrier
	s_add_u32 s60, s60, 0x100
	s_addc_u32 s61, s61, 0
	s_add_i32 s62, s62, 1
	s_cmp_gt_u32 s63, 37
	s_mov_b64 s[12:13], s[14:15]
	s_mov_b32 s63, s64
	s_cbranch_scc1 .LBB0_1032

.LBB0_1099:
	s_add_u32 s18, s16, 0xfffc0080
	s_addc_u32 s19, s17, -1
	s_add_i32 s46, 0, 0x10000
	s_cmp_eq_u32 s45, 12
	s_cselect_b32 s21, s5, s19
	s_cselect_b32 s20, s9, s18
	s_cselect_b32 s19, s11, s44
	s_cselect_b32 s18, s42, s43
	s_add_i32 s48, 0, 0x14000
	v_add_u32_e32 v154, s46, v140
	v_add_u32_e32 v170, s48, v140
	ds_read_b128 v[142:145], v154
	ds_read_b128 v[146:149], v154 offset:1024
	ds_read_b128 v[150:153], v154 offset:2048
	ds_read_b128 v[154:157], v154 offset:3072
	ds_read_b128 v[158:161], v170
	ds_read_b128 v[162:165], v170 offset:1024
	ds_read_b128 v[166:169], v170 offset:2048
	ds_read_b128 v[170:173], v170 offset:3072
	v_lshl_add_u64 v[190:191], s[16:17], 0, v[136:137]
	s_add_i32 m0, s28, 0xc000
	ds_read_b128 v[174:177], v141
	ds_read_b128 v[178:181], v141 offset:1024
	ds_read_b128 v[182:185], v141 offset:2048
	ds_read_b128 v[186:189], v141 offset:3072
	ds_read_b128 v[194:197], v141 offset:4096
	ds_read_b128 v[198:201], v141 offset:5120
	ds_read_b128 v[202:205], v141 offset:6144
	ds_read_b128 v[220:223], v141 offset:7168
	global_load_lds_dwordx4 v[190:191], off
	v_lshl_add_u64 v[190:191], s[16:17], 0, v[134:135]
	s_add_i32 m0, s28, 0xe000
	s_nop 0
	global_load_lds_dwordx4 v[190:191], off
	s_waitcnt vmcnt(8)
	s_waitcnt lgkmcnt(0)
	s_barrier
	s_waitcnt lgkmcnt(0)
	v_mfma_f32_16x16x32_bf16 v[124:127], v[142:145], v[174:177], v[124:127]
	v_mfma_f32_16x16x32_bf16 v[120:123], v[150:153], v[174:177], v[120:123]
	v_mfma_f32_16x16x32_bf16 v[116:119], v[142:145], v[182:185], v[116:119]
	v_mfma_f32_16x16x32_bf16 v[112:115], v[150:153], v[182:185], v[112:115]
	v_mfma_f32_16x16x32_bf16 v[100:103], v[142:145], v[194:197], v[100:103]
	v_mfma_f32_16x16x32_bf16 v[96:99], v[150:153], v[194:197], v[96:99]
	v_mfma_f32_16x16x32_bf16 v[84:87], v[142:145], v[202:205], v[84:87]
	v_mfma_f32_16x16x32_bf16 v[80:83], v[150:153], v[202:205], v[80:83]
	v_mfma_f32_16x16x32_bf16 v[124:127], v[146:149], v[178:181], v[124:127]
	v_mfma_f32_16x16x32_bf16 v[120:123], v[154:157], v[178:181], v[120:123]
	v_mfma_f32_16x16x32_bf16 v[116:119], v[146:149], v[186:189], v[116:119]
	v_mfma_f32_16x16x32_bf16 v[112:115], v[154:157], v[186:189], v[112:115]
	v_mfma_f32_16x16x32_bf16 v[100:103], v[146:149], v[198:201], v[100:103]
	v_mfma_f32_16x16x32_bf16 v[96:99], v[154:157], v[198:201], v[96:99]
	v_mfma_f32_16x16x32_bf16 v[84:87], v[146:149], v[220:223], v[84:87]
	v_mfma_f32_16x16x32_bf16 v[80:83], v[154:157], v[220:223], v[80:83]
	v_mfma_f32_16x16x32_bf16 v[108:111], v[158:161], v[174:177], v[108:111]
	v_mfma_f32_16x16x32_bf16 v[104:107], v[166:169], v[174:177], v[104:107]
	v_mfma_f32_16x16x32_bf16 v[92:95], v[158:161], v[182:185], v[92:95]
	v_mfma_f32_16x16x32_bf16 v[88:91], v[166:169], v[182:185], v[88:91]
	v_mfma_f32_16x16x32_bf16 v[76:79], v[158:161], v[194:197], v[76:79]
	v_mfma_f32_16x16x32_bf16 v[72:75], v[166:169], v[194:197], v[72:75]
	v_mfma_f32_16x16x32_bf16 v[68:71], v[158:161], v[202:205], v[68:71]
	v_mfma_f32_16x16x32_bf16 v[64:67], v[166:169], v[202:205], v[64:67]
	v_mfma_f32_16x16x32_bf16 v[108:111], v[162:165], v[178:181], v[108:111]
	v_mfma_f32_16x16x32_bf16 v[104:107], v[170:173], v[178:181], v[104:107]
	v_mfma_f32_16x16x32_bf16 v[92:95], v[162:165], v[186:189], v[92:95]
	v_mfma_f32_16x16x32_bf16 v[88:91], v[170:173], v[186:189], v[88:91]
	v_mfma_f32_16x16x32_bf16 v[76:79], v[162:165], v[198:201], v[76:79]
	v_mfma_f32_16x16x32_bf16 v[72:75], v[170:173], v[198:201], v[72:75]
	v_mfma_f32_16x16x32_bf16 v[68:71], v[162:165], v[220:223], v[68:71]
	v_mfma_f32_16x16x32_bf16 v[64:67], v[170:173], v[220:223], v[64:67]
	s_barrier
	s_add_i32 s46, s46, s27
	v_lshl_add_u64 v[190:191], s[18:19], 0, v[192:193]
	s_mov_b32 m0, s46
	ds_read_b128 v[174:177], v141 offset:16384
	ds_read_b128 v[178:181], v141 offset:17408
	ds_read_b128 v[182:185], v141 offset:18432
	ds_read_b128 v[186:189], v141 offset:19456
	ds_read_b128 v[194:197], v141 offset:20480
	ds_read_b128 v[198:201], v141 offset:21504
	ds_read_b128 v[202:205], v141 offset:22528
	ds_read_b128 v[220:223], v141 offset:23552
	global_load_lds_dwordx4 v[190:191], off
	s_add_i32 m0, s46, 0x2000
	s_add_u32 s46, s18, 0x40000
	v_lshl_add_u64 v[224:225], s[18:19], 0, v[132:133]
	s_addc_u32 s47, s19, 0
	s_add_i32 s48, s48, s27
	global_load_lds_dwordx4 v[224:225], off
	v_lshl_add_u64 v[226:227], s[46:47], 0, v[192:193]
	s_mov_b32 m0, s48
	v_lshl_add_u64 v[228:229], s[20:21], 0, v[130:131]
	global_load_lds_dwordx4 v[226:227], off
	v_lshl_add_u64 v[226:227], s[46:47], 0, v[132:133]
	s_add_i32 m0, s48, 0x2000
	s_nop 0
	global_load_lds_dwordx4 v[226:227], off
	v_lshl_add_u64 v[226:227], s[20:21], 0, v[128:129]
	s_mov_b32 m0, s28
	s_nop 0
	global_load_lds_dwordx4 v[226:227], off
	s_mov_b32 m0, s29
	s_nop 0
	global_load_lds_dwordx4 v[228:229], off
	s_waitcnt vmcnt(8)
	s_waitcnt lgkmcnt(0)
	s_barrier
	s_waitcnt lgkmcnt(0)
	v_mfma_f32_16x16x32_bf16 v[60:63], v[142:145], v[174:177], v[60:63]
	v_mfma_f32_16x16x32_bf16 v[56:59], v[150:153], v[174:177], v[56:59]
	v_mfma_f32_16x16x32_bf16 v[52:55], v[142:145], v[182:185], v[52:55]
	v_mfma_f32_16x16x32_bf16 v[48:51], v[150:153], v[182:185], v[48:51]
	v_mfma_f32_16x16x32_bf16 v[36:39], v[142:145], v[194:197], v[36:39]
	v_mfma_f32_16x16x32_bf16 v[32:35], v[150:153], v[194:197], v[32:35]
	v_mfma_f32_16x16x32_bf16 v[20:23], v[142:145], v[202:205], v[20:23]
	v_mfma_f32_16x16x32_bf16 v[16:19], v[150:153], v[202:205], v[16:19]
	v_mfma_f32_16x16x32_bf16 v[60:63], v[146:149], v[178:181], v[60:63]
	v_mfma_f32_16x16x32_bf16 v[56:59], v[154:157], v[178:181], v[56:59]
	v_mfma_f32_16x16x32_bf16 v[52:55], v[146:149], v[186:189], v[52:55]
	v_mfma_f32_16x16x32_bf16 v[48:51], v[154:157], v[186:189], v[48:51]
	v_mfma_f32_16x16x32_bf16 v[36:39], v[146:149], v[198:201], v[36:39]
	v_mfma_f32_16x16x32_bf16 v[32:35], v[154:157], v[198:201], v[32:35]
	v_mfma_f32_16x16x32_bf16 v[20:23], v[146:149], v[220:223], v[20:23]
	v_mfma_f32_16x16x32_bf16 v[16:19], v[154:157], v[220:223], v[16:19]
	v_mfma_f32_16x16x32_bf16 v[44:47], v[158:161], v[174:177], v[44:47]
	v_mfma_f32_16x16x32_bf16 v[40:43], v[166:169], v[174:177], v[40:43]
	v_mfma_f32_16x16x32_bf16 v[28:31], v[158:161], v[182:185], v[28:31]
	v_mfma_f32_16x16x32_bf16 v[24:27], v[166:169], v[182:185], v[24:27]
	v_mfma_f32_16x16x32_bf16 v[12:15], v[158:161], v[194:197], v[12:15]
	v_mfma_f32_16x16x32_bf16 v[8:11], v[166:169], v[194:197], v[8:11]
	v_mfma_f32_16x16x32_bf16 v[4:7], v[158:161], v[202:205], v[4:7]
	v_mfma_f32_16x16x32_bf16 v[0:3], v[166:169], v[202:205], v[0:3]
	v_mfma_f32_16x16x32_bf16 v[44:47], v[162:165], v[178:181], v[44:47]
	v_mfma_f32_16x16x32_bf16 v[40:43], v[170:173], v[178:181], v[40:43]
	v_mfma_f32_16x16x32_bf16 v[28:31], v[162:165], v[186:189], v[28:31]
	v_mfma_f32_16x16x32_bf16 v[24:27], v[170:173], v[186:189], v[24:27]
	v_mfma_f32_16x16x32_bf16 v[12:15], v[162:165], v[198:201], v[12:15]
	v_mfma_f32_16x16x32_bf16 v[8:11], v[170:173], v[198:201], v[8:11]
	v_mfma_f32_16x16x32_bf16 v[4:7], v[162:165], v[220:223], v[4:7]
	v_mfma_f32_16x16x32_bf16 v[0:3], v[170:173], v[220:223], v[0:3]
	s_barrier
	s_add_i32 s46, 0, 0x18000
	s_add_i32 s47, 0, 0x1c000
	v_add_u32_e32 v154, s46, v140
	v_add_u32_e32 v170, s47, v140
	ds_read_b128 v[142:145], v154
	ds_read_b128 v[146:149], v154 offset:1024
	ds_read_b128 v[150:153], v154 offset:2048
	ds_read_b128 v[154:157], v154 offset:3072
	ds_read_b128 v[158:161], v170
	ds_read_b128 v[162:165], v170 offset:1024
	ds_read_b128 v[166:169], v170 offset:2048
	ds_read_b128 v[170:173], v170 offset:3072
	s_add_u32 s20, s20, 0x40000
	s_addc_u32 s21, s21, 0
	s_mov_b32 m0, s30
	v_lshl_add_u64 v[230:231], s[20:21], 0, v[128:129]
	ds_read_b128 v[174:177], v141 offset:32768
	ds_read_b128 v[178:181], v141 offset:33792
	ds_read_b128 v[182:185], v141 offset:34816
	ds_read_b128 v[186:189], v141 offset:35840
	ds_read_b128 v[194:197], v141 offset:36864
	ds_read_b128 v[198:201], v141 offset:37888
	ds_read_b128 v[202:205], v141 offset:38912
	ds_read_b128 v[220:223], v141 offset:39936
	global_load_lds_dwordx4 v[230:231], off
	v_lshl_add_u64 v[230:231], s[20:21], 0, v[130:131]
	s_mov_b32 m0, s31
	s_nop 0
	global_load_lds_dwordx4 v[230:231], off
	s_waitcnt vmcnt(8)
	s_waitcnt lgkmcnt(0)
	s_barrier
	s_waitcnt lgkmcnt(0)
	v_mfma_f32_16x16x32_bf16 v[124:127], v[142:145], v[174:177], v[124:127]
	v_mfma_f32_16x16x32_bf16 v[120:123], v[150:153], v[174:177], v[120:123]
	v_mfma_f32_16x16x32_bf16 v[116:119], v[142:145], v[182:185], v[116:119]
	v_mfma_f32_16x16x32_bf16 v[112:115], v[150:153], v[182:185], v[112:115]
	v_mfma_f32_16x16x32_bf16 v[100:103], v[142:145], v[194:197], v[100:103]
	v_mfma_f32_16x16x32_bf16 v[96:99], v[150:153], v[194:197], v[96:99]
	v_mfma_f32_16x16x32_bf16 v[84:87], v[142:145], v[202:205], v[84:87]
	v_mfma_f32_16x16x32_bf16 v[80:83], v[150:153], v[202:205], v[80:83]
	v_mfma_f32_16x16x32_bf16 v[124:127], v[146:149], v[178:181], v[124:127]
	v_mfma_f32_16x16x32_bf16 v[120:123], v[154:157], v[178:181], v[120:123]
	v_mfma_f32_16x16x32_bf16 v[116:119], v[146:149], v[186:189], v[116:119]
	v_mfma_f32_16x16x32_bf16 v[112:115], v[154:157], v[186:189], v[112:115]
	v_mfma_f32_16x16x32_bf16 v[100:103], v[146:149], v[198:201], v[100:103]
	v_mfma_f32_16x16x32_bf16 v[96:99], v[154:157], v[198:201], v[96:99]
	v_mfma_f32_16x16x32_bf16 v[84:87], v[146:149], v[220:223], v[84:87]
	v_mfma_f32_16x16x32_bf16 v[80:83], v[154:157], v[220:223], v[80:83]
	v_mfma_f32_16x16x32_bf16 v[108:111], v[158:161], v[174:177], v[108:111]
	v_mfma_f32_16x16x32_bf16 v[104:107], v[166:169], v[174:177], v[104:107]
	v_mfma_f32_16x16x32_bf16 v[92:95], v[158:161], v[182:185], v[92:95]
	v_mfma_f32_16x16x32_bf16 v[88:91], v[166:169], v[182:185], v[88:91]
	v_mfma_f32_16x16x32_bf16 v[76:79], v[158:161], v[194:197], v[76:79]
	v_mfma_f32_16x16x32_bf16 v[72:75], v[166:169], v[194:197], v[72:75]
	v_mfma_f32_16x16x32_bf16 v[68:71], v[158:161], v[202:205], v[68:71]
	v_mfma_f32_16x16x32_bf16 v[64:67], v[166:169], v[202:205], v[64:67]
	v_mfma_f32_16x16x32_bf16 v[108:111], v[162:165], v[178:181], v[108:111]
	v_mfma_f32_16x16x32_bf16 v[104:107], v[170:173], v[178:181], v[104:107]
	v_mfma_f32_16x16x32_bf16 v[92:95], v[162:165], v[186:189], v[92:95]
	v_mfma_f32_16x16x32_bf16 v[88:91], v[170:173], v[186:189], v[88:91]
	v_mfma_f32_16x16x32_bf16 v[76:79], v[162:165], v[198:201], v[76:79]
	v_mfma_f32_16x16x32_bf16 v[72:75], v[170:173], v[198:201], v[72:75]
	v_mfma_f32_16x16x32_bf16 v[68:71], v[162:165], v[220:223], v[68:71]
	v_mfma_f32_16x16x32_bf16 v[64:67], v[170:173], v[220:223], v[64:67]
	s_barrier
	s_add_i32 s20, s46, s27
	v_lshl_add_u64 v[190:191], v[190:191], 0, s[76:77]
	s_mov_b32 m0, s20
	ds_read_b128 v[174:177], v141 offset:49152
	ds_read_b128 v[178:181], v141 offset:50176
	ds_read_b128 v[182:185], v141 offset:51200
	ds_read_b128 v[186:189], v141 offset:52224
	ds_read_b128 v[194:197], v141 offset:53248
	ds_read_b128 v[198:201], v141 offset:54272
	ds_read_b128 v[202:205], v141 offset:55296
	ds_read_b128 v[220:223], v141 offset:56320
	global_load_lds_dwordx4 v[190:191], off
	s_add_i32 m0, s20, 0x2000
	s_add_u32 s18, s18, 0x40080
	v_lshl_add_u64 v[190:191], v[224:225], 0, s[76:77]
	s_addc_u32 s19, s19, 0
	s_add_i32 s20, s47, s27
	global_load_lds_dwordx4 v[190:191], off
	v_lshl_add_u64 v[190:191], s[18:19], 0, v[192:193]
	s_mov_b32 m0, s20
	s_nop 0
	global_load_lds_dwordx4 v[190:191], off
	v_lshl_add_u64 v[190:191], s[18:19], 0, v[132:133]
	s_add_i32 m0, s20, 0x2000
	s_nop 0
	global_load_lds_dwordx4 v[190:191], off
	v_lshl_add_u64 v[190:191], v[226:227], 0, s[76:77]
	s_mov_b32 m0, s36
	s_nop 0
	global_load_lds_dwordx4 v[190:191], off
	v_lshl_add_u64 v[190:191], v[228:229], 0, s[76:77]
	s_mov_b32 m0, s37
	s_nop 0
	global_load_lds_dwordx4 v[190:191], off
	s_waitcnt vmcnt(8)
	s_waitcnt lgkmcnt(0)
	s_barrier
	s_waitcnt lgkmcnt(0)
	v_mfma_f32_16x16x32_bf16 v[60:63], v[142:145], v[174:177], v[60:63]
	v_mfma_f32_16x16x32_bf16 v[56:59], v[150:153], v[174:177], v[56:59]
	v_mfma_f32_16x16x32_bf16 v[52:55], v[142:145], v[182:185], v[52:55]
	v_mfma_f32_16x16x32_bf16 v[48:51], v[150:153], v[182:185], v[48:51]
	v_mfma_f32_16x16x32_bf16 v[36:39], v[142:145], v[194:197], v[36:39]
	v_mfma_f32_16x16x32_bf16 v[32:35], v[150:153], v[194:197], v[32:35]
	v_mfma_f32_16x16x32_bf16 v[20:23], v[142:145], v[202:205], v[20:23]
	v_mfma_f32_16x16x32_bf16 v[16:19], v[150:153], v[202:205], v[16:19]
	v_mfma_f32_16x16x32_bf16 v[60:63], v[146:149], v[178:181], v[60:63]
	v_mfma_f32_16x16x32_bf16 v[56:59], v[154:157], v[178:181], v[56:59]
	v_mfma_f32_16x16x32_bf16 v[52:55], v[146:149], v[186:189], v[52:55]
	v_mfma_f32_16x16x32_bf16 v[48:51], v[154:157], v[186:189], v[48:51]
	v_mfma_f32_16x16x32_bf16 v[36:39], v[146:149], v[198:201], v[36:39]
	v_mfma_f32_16x16x32_bf16 v[32:35], v[154:157], v[198:201], v[32:35]
	v_mfma_f32_16x16x32_bf16 v[20:23], v[146:149], v[220:223], v[20:23]
	v_mfma_f32_16x16x32_bf16 v[16:19], v[154:157], v[220:223], v[16:19]
	v_mfma_f32_16x16x32_bf16 v[44:47], v[158:161], v[174:177], v[44:47]
	v_mfma_f32_16x16x32_bf16 v[40:43], v[166:169], v[174:177], v[40:43]
	v_mfma_f32_16x16x32_bf16 v[28:31], v[158:161], v[182:185], v[28:31]
	v_mfma_f32_16x16x32_bf16 v[24:27], v[166:169], v[182:185], v[24:27]
	v_mfma_f32_16x16x32_bf16 v[12:15], v[158:161], v[194:197], v[12:15]
	v_mfma_f32_16x16x32_bf16 v[8:11], v[166:169], v[194:197], v[8:11]
	v_mfma_f32_16x16x32_bf16 v[4:7], v[158:161], v[202:205], v[4:7]
	v_mfma_f32_16x16x32_bf16 v[0:3], v[166:169], v[202:205], v[0:3]
	v_mfma_f32_16x16x32_bf16 v[44:47], v[162:165], v[178:181], v[44:47]
	v_mfma_f32_16x16x32_bf16 v[40:43], v[170:173], v[178:181], v[40:43]
	v_mfma_f32_16x16x32_bf16 v[28:31], v[162:165], v[186:189], v[28:31]
	v_mfma_f32_16x16x32_bf16 v[24:27], v[170:173], v[186:189], v[24:27]
	v_mfma_f32_16x16x32_bf16 v[12:15], v[162:165], v[198:201], v[12:15]
	v_mfma_f32_16x16x32_bf16 v[8:11], v[170:173], v[198:201], v[8:11]
	v_mfma_f32_16x16x32_bf16 v[4:7], v[162:165], v[220:223], v[4:7]
	v_mfma_f32_16x16x32_bf16 v[0:3], v[170:173], v[220:223], v[0:3]
	s_barrier
	s_add_i32 s45, s45, 2
	s_add_u32 s43, s43, 0x100
	s_addc_u32 s44, s44, 0
	s_add_u32 s16, s16, 0x100
	s_addc_u32 s17, s17, 0
	s_cmp_gt_u32 s45, 13
	s_cbranch_scc0 .LBB0_1099
	s_and_b64 vcc, exec, s[2:3]
	s_cbranch_vccz .LBB0_1102
	s_barrier
